# S3 gelu and GLU sigmoid/silu epilogues: IEEE f32 division expansion replaced by v_rcp_f32 (f32, ~1 ulp) on top of fused S1 scan
# speedup vs baseline: 1.0438x; 1.0168x over previous
; __device__ __forceinline__ unsigned cvt_pk_bf16(float lo, float hi) { unsigned r; asm volatile("v_cvt_pk_bf16_f32 %0, %1, %2" : "=v"(r) : "v"(lo), "v"(hi)); return r; }
; __device__ __forceinline__ float gelu_tanh_f(float y) { const float t = 0.7978845608028654f * (y + 0.044715f * y * y * y); return y * sigmoid_f(2.0f * t); }
; __device__ __forceinline__ float silu_f(float z) { return z / (1.0f + __expf(-z)); }
; __device__ __forceinline__ float sigmoid_f(float z) { return 1.0f / (1.0f + __expf(-z)); }
;     __device__ __forceinline__ void operator()(const AccT& acc, const Unit& u, int wr, int wc, int fr, int fq) const {
;     ...
;                     u32x4 w; w.x = cvt_pk_bf16(gelu_tanh_f(v0[0]), gelu_tanh_f(v0[1])); w.y = cvt_pk_bf16(gelu_tanh_f(v0[2]), gelu_tanh_f(v0[3]));
;                     w.z = cvt_pk_bf16(gelu_tanh_f(v1[0]), gelu_tanh_f(v1[1])); w.w = cvt_pk_bf16(gelu_tanh_f(v1[2]), gelu_tanh_f(v1[3]));
;                     *(u32x4*)(YG + ((size_t)rg * 32 + i) * 1024 + u.g * 16 + s0) = w;
.LBB0_537:
	s_lshl_b32 s24, s89, 8
	v_add_u32_e32 v140, s24, v144
	v_ashrrev_i32_e32 v141, 31, v140
	v_lshlrev_b64 v[142:143], 16, v[140:141]
	v_mul_f32_e32 v141, 0x3d372713, v124
	v_mul_f32_e32 v141, v124, v141
	v_fma_f32 v141, v124, v141, v124
	v_mul_f32_e32 v141, 0x3f4c422a, v141
	v_add_f32_e32 v141, v141, v141
	v_mul_f32_e32 v141, 0xbfb8aa3b, v141
	v_exp_f32_e32 v141, v141
	v_lshl_or_b32 v140, s38, 8, v153
	v_ashrrev_i32_e32 v140, 4, v140
	v_add_f32_e32 v141, 1.0, v141
	v_rcp_f32_e32 v141, v141
	s_nop 0
	v_mul_f32_e32 v124, v124, v141
	v_mul_f32_e32 v141, 0x3d372713, v125
	v_mul_f32_e32 v141, v125, v141
	v_fma_f32 v141, v125, v141, v125
	v_mul_f32_e32 v141, 0x3f4c422a, v141
	v_add_f32_e32 v141, v141, v141
	v_mul_f32_e32 v141, 0xbfb8aa3b, v141
	v_exp_f32_e32 v141, v141
	s_nop 0
	v_add_f32_e32 v141, 1.0, v141
	v_rcp_f32_e32 v141, v141
	s_nop 0
	v_mul_f32_e32 v125, v125, v141
	v_cvt_pk_bf16_f32 v124, v124, v125
	v_mul_f32_e32 v125, 0x3d372713, v126
	v_mul_f32_e32 v125, v126, v125
	v_fma_f32 v125, v126, v125, v126
	v_mul_f32_e32 v125, 0x3f4c422a, v125
	v_add_f32_e32 v125, v125, v125
	v_mul_f32_e32 v125, 0xbfb8aa3b, v125
	v_exp_f32_e32 v125, v125
	s_nop 0
	v_add_f32_e32 v125, 1.0, v125
	v_rcp_f32_e32 v125, v125
	s_nop 0
	v_mul_f32_e32 v125, v126, v125
	v_mul_f32_e32 v126, 0x3d372713, v127
	v_mul_f32_e32 v126, v127, v126
	v_fma_f32 v126, v127, v126, v127
	v_mul_f32_e32 v126, 0x3f4c422a, v126
	v_add_f32_e32 v126, v126, v126
	v_mul_f32_e32 v126, 0xbfb8aa3b, v126
	v_exp_f32_e32 v126, v126
	s_nop 0
	v_add_f32_e32 v126, 1.0, v126
	v_rcp_f32_e32 v126, v126
	s_nop 0
	v_mul_f32_e32 v126, v127, v126
	v_cvt_pk_bf16_f32 v125, v125, v126
	v_mul_f32_e32 v126, 0x3d372713, v120
	v_mul_f32_e32 v126, v120, v126
	v_fma_f32 v126, v120, v126, v120
	v_mul_f32_e32 v126, 0x3f4c422a, v126
	v_add_f32_e32 v126, v126, v126
	v_mul_f32_e32 v126, 0xbfb8aa3b, v126
	v_exp_f32_e32 v126, v126
	s_nop 0
	v_add_f32_e32 v126, 1.0, v126
	v_rcp_f32_e32 v126, v126
	s_nop 0
	v_mul_f32_e32 v120, v120, v126
	v_mul_f32_e32 v126, 0x3d372713, v121
	v_mul_f32_e32 v126, v121, v126
	v_fma_f32 v126, v121, v126, v121
	v_mul_f32_e32 v126, 0x3f4c422a, v126
	v_add_f32_e32 v126, v126, v126
	v_mul_f32_e32 v126, 0xbfb8aa3b, v126
	v_exp_f32_e32 v126, v126
	s_nop 0
	v_add_f32_e32 v126, 1.0, v126
	v_rcp_f32_e32 v126, v126
	s_nop 0
	v_mul_f32_e32 v121, v121, v126
	v_cvt_pk_bf16_f32 v126, v120, v121
	v_mul_f32_e32 v120, 0x3d372713, v122
	v_mul_f32_e32 v120, v122, v120
	v_fma_f32 v120, v122, v120, v122
	v_mul_f32_e32 v120, 0x3f4c422a, v120
	v_add_f32_e32 v120, v120, v120
	v_mul_f32_e32 v120, 0xbfb8aa3b, v120
	v_exp_f32_e32 v120, v120
	s_nop 0
	v_add_f32_e32 v120, 1.0, v120
	v_rcp_f32_e32 v120, v120
	s_nop 0
	v_mul_f32_e32 v121, 0x3d372713, v123
	v_mul_f32_e32 v121, v123, v121
	v_fma_f32 v121, v123, v121, v123
	v_mul_f32_e32 v121, 0x3f4c422a, v121
	v_add_f32_e32 v121, v121, v121
	v_mul_f32_e32 v121, 0xbfb8aa3b, v121
	v_exp_f32_e32 v121, v121
	v_mul_f32_e32 v120, v122, v120
	v_add_f32_e32 v121, 1.0, v121
	s_lshl_b32 s22, s37, 4
	s_ashr_i32 s23, s22, 31
	s_lshl_b64 s[22:23], s[22:23], 1
	v_rcp_f32_e32 v121, v121
	s_nop 0
	v_mul_f32_e32 v121, v123, v121
	v_ashrrev_i32_e32 v141, 31, v140
	v_cvt_pk_bf16_f32 v127, v120, v121
	v_lshl_add_u64 v[122:123], s[8:9], 0, v[142:143]
	v_lshlrev_b64 v[120:121], 11, v[140:141]
	v_lshl_add_u64 v[142:143], v[122:123], 0, v[120:121]
	v_lshl_add_u64 v[142:143], v[142:143], 0, s[22:23]
	v_lshl_add_u64 v[142:143], v[142:143], 0, v[224:225]
	global_store_dwordx4 v[142:143], v[124:127], off
	s_nop 1
	v_mul_f32_e32 v125, 0x3d372713, v116
	v_mul_f32_e32 v125, v116, v125
	v_fma_f32 v125, v116, v125, v116
	v_mul_f32_e32 v125, 0x3f4c422a, v125
	v_add_f32_e32 v125, v125, v125
	v_mul_f32_e32 v125, 0xbfb8aa3b, v125
	v_exp_f32_e32 v125, v125
	v_or_b32_e32 v124, 8, v140
	v_add_f32_e32 v125, 1.0, v125
	v_rcp_f32_e32 v125, v125
	s_nop 0
	v_mul_f32_e32 v116, v116, v125
	v_mul_f32_e32 v125, 0x3d372713, v117
	v_mul_f32_e32 v125, v117, v125
	v_fma_f32 v125, v117, v125, v117
	v_mul_f32_e32 v125, 0x3f4c422a, v125
	v_add_f32_e32 v125, v125, v125
	v_mul_f32_e32 v125, 0xbfb8aa3b, v125
	v_exp_f32_e32 v125, v125
	s_nop 0
	v_add_f32_e32 v125, 1.0, v125
	v_rcp_f32_e32 v125, v125
	s_nop 0
	v_mul_f32_e32 v117, v117, v125
	v_cvt_pk_bf16_f32 v116, v116, v117
	v_mul_f32_e32 v117, 0x3d372713, v118
	v_mul_f32_e32 v117, v118, v117
	v_fma_f32 v117, v118, v117, v118
	v_mul_f32_e32 v117, 0x3f4c422a, v117
	v_add_f32_e32 v117, v117, v117
	v_mul_f32_e32 v117, 0xbfb8aa3b, v117
	v_exp_f32_e32 v117, v117
	s_nop 0
	v_add_f32_e32 v117, 1.0, v117
	v_rcp_f32_e32 v117, v117
	s_nop 0
	v_mul_f32_e32 v117, v118, v117
	v_mul_f32_e32 v118, 0x3d372713, v119
	v_mul_f32_e32 v118, v119, v118
	v_fma_f32 v118, v119, v118, v119
	v_mul_f32_e32 v118, 0x3f4c422a, v118
	v_add_f32_e32 v118, v118, v118
	v_mul_f32_e32 v118, 0xbfb8aa3b, v118
	v_exp_f32_e32 v118, v118
	s_nop 0
	v_add_f32_e32 v118, 1.0, v118
	v_rcp_f32_e32 v118, v118
	s_nop 0
	v_mul_f32_e32 v118, v119, v118
	v_cvt_pk_bf16_f32 v117, v117, v118
	v_mul_f32_e32 v118, 0x3d372713, v112
	v_mul_f32_e32 v118, v112, v118
	v_fma_f32 v118, v112, v118, v112
	v_mul_f32_e32 v118, 0x3f4c422a, v118
	v_add_f32_e32 v118, v118, v118
	v_mul_f32_e32 v118, 0xbfb8aa3b, v118
	v_exp_f32_e32 v118, v118
	s_nop 0
	v_add_f32_e32 v118, 1.0, v118
	v_rcp_f32_e32 v118, v118
	s_nop 0
	v_mul_f32_e32 v112, v112, v118
	v_mul_f32_e32 v118, 0x3d372713, v113
	v_mul_f32_e32 v118, v113, v118
	v_fma_f32 v118, v113, v118, v113
	v_mul_f32_e32 v118, 0x3f4c422a, v118
	v_add_f32_e32 v118, v118, v118
	v_mul_f32_e32 v118, 0xbfb8aa3b, v118
	v_exp_f32_e32 v118, v118
	s_nop 0
	v_add_f32_e32 v118, 1.0, v118
	v_rcp_f32_e32 v118, v118
; __device__ __forceinline__ unsigned cvt_pk_bf16(float lo, float hi) { unsigned r; asm volatile("v_cvt_pk_bf16_f32 %0, %1, %2" : "=v"(r) : "v"(lo), "v"(hi)); return r; }
; __device__ __forceinline__ float gelu_tanh_f(float y) { const float t = 0.7978845608028654f * (y + 0.044715f * y * y * y); return y * sigmoid_f(2.0f * t); }
; __device__ __forceinline__ float silu_f(float z) { return z / (1.0f + __expf(-z)); }
; __device__ __forceinline__ float sigmoid_f(float z) { return 1.0f / (1.0f + __expf(-z)); }
;     __device__ __forceinline__ void operator()(const AccT& acc, const Unit& u, int wr, int wc, int fr, int fq) const {
;     ...
;                     u32x4 w; w.x = cvt_pk_bf16(gelu_tanh_f(v0[0]), gelu_tanh_f(v0[1])); w.y = cvt_pk_bf16(gelu_tanh_f(v0[2]), gelu_tanh_f(v0[3]));
;                     w.z = cvt_pk_bf16(gelu_tanh_f(v1[0]), gelu_tanh_f(v1[1])); w.w = cvt_pk_bf16(gelu_tanh_f(v1[2]), gelu_tanh_f(v1[3]));
;                     *(u32x4*)(YG + ((size_t)rg * 32 + i) * 1024 + u.g * 16 + s0) = w;
	s_nop 0
	v_mul_f32_e32 v113, v113, v118
	v_cvt_pk_bf16_f32 v118, v112, v113
	v_mul_f32_e32 v112, 0x3d372713, v114
	v_mul_f32_e32 v112, v114, v112
	v_fma_f32 v112, v114, v112, v114
	v_mul_f32_e32 v112, 0x3f4c422a, v112
	v_add_f32_e32 v112, v112, v112
	v_mul_f32_e32 v112, 0xbfb8aa3b, v112
	v_exp_f32_e32 v112, v112
	s_nop 0
	v_add_f32_e32 v112, 1.0, v112
	v_rcp_f32_e32 v112, v112
	s_nop 0
	v_mul_f32_e32 v113, 0x3d372713, v115
	v_mul_f32_e32 v113, v115, v113
	v_fma_f32 v113, v115, v113, v115
	v_mul_f32_e32 v113, 0x3f4c422a, v113
	v_add_f32_e32 v113, v113, v113
	v_mul_f32_e32 v113, 0xbfb8aa3b, v113
	v_exp_f32_e32 v113, v113
	v_mul_f32_e32 v112, v114, v112
	v_add_f32_e32 v113, 1.0, v113
	v_rcp_f32_e32 v113, v113
	s_nop 0
	v_mul_f32_e32 v113, v115, v113
	v_ashrrev_i32_e32 v125, 31, v124
	v_cvt_pk_bf16_f32 v119, v112, v113
	v_lshlrev_b64 v[112:113], 11, v[124:125]
	v_lshl_add_u64 v[114:115], v[122:123], 0, v[112:113]
	v_lshl_add_u64 v[114:115], v[114:115], 0, s[22:23]
	v_lshl_add_u64 v[114:115], v[114:115], 0, v[224:225]
	global_store_dwordx4 v[114:115], v[116:119], off
	v_add_u32_e32 v114, s24, v146
	v_ashrrev_i32_e32 v115, 31, v114
	v_mul_f32_e32 v116, 0x3d372713, v108
	v_mul_f32_e32 v116, v108, v116
	v_fma_f32 v116, v108, v116, v108
	v_mul_f32_e32 v116, 0x3f4c422a, v116
	v_add_f32_e32 v116, v116, v116
	v_mul_f32_e32 v116, 0xbfb8aa3b, v116
	v_exp_f32_e32 v116, v116
	v_lshlrev_b64 v[114:115], 16, v[114:115]
	v_add_f32_e32 v116, 1.0, v116
	v_rcp_f32_e32 v116, v116
	s_nop 0
	v_mul_f32_e32 v108, v108, v116
	v_mul_f32_e32 v116, 0x3d372713, v109
	v_mul_f32_e32 v116, v109, v116
	v_fma_f32 v116, v109, v116, v109
	v_mul_f32_e32 v116, 0x3f4c422a, v116
	v_add_f32_e32 v116, v116, v116
	v_mul_f32_e32 v116, 0xbfb8aa3b, v116
	v_exp_f32_e32 v116, v116
	s_nop 0
	v_add_f32_e32 v116, 1.0, v116
	v_rcp_f32_e32 v116, v116
	s_nop 0
	v_mul_f32_e32 v109, v109, v116
	v_cvt_pk_bf16_f32 v108, v108, v109
	v_mul_f32_e32 v109, 0x3d372713, v110
	v_mul_f32_e32 v109, v110, v109
	v_fma_f32 v109, v110, v109, v110
	v_mul_f32_e32 v109, 0x3f4c422a, v109
	v_add_f32_e32 v109, v109, v109
	v_mul_f32_e32 v109, 0xbfb8aa3b, v109
	v_exp_f32_e32 v109, v109
	s_nop 0
	v_add_f32_e32 v109, 1.0, v109
	v_rcp_f32_e32 v109, v109
	s_nop 0
	v_mul_f32_e32 v109, v110, v109
	v_mul_f32_e32 v110, 0x3d372713, v111
	v_mul_f32_e32 v110, v111, v110
	v_fma_f32 v110, v111, v110, v111
	v_mul_f32_e32 v110, 0x3f4c422a, v110
	v_add_f32_e32 v110, v110, v110
	v_mul_f32_e32 v110, 0xbfb8aa3b, v110
	v_exp_f32_e32 v110, v110
	s_nop 0
	v_add_f32_e32 v110, 1.0, v110
	v_rcp_f32_e32 v110, v110
	s_nop 0
	v_mul_f32_e32 v110, v111, v110
	v_cvt_pk_bf16_f32 v109, v109, v110
	v_mul_f32_e32 v110, 0x3d372713, v104
	v_mul_f32_e32 v110, v104, v110
	v_fma_f32 v110, v104, v110, v104
	v_mul_f32_e32 v110, 0x3f4c422a, v110
	v_add_f32_e32 v110, v110, v110
	v_mul_f32_e32 v110, 0xbfb8aa3b, v110
	v_exp_f32_e32 v110, v110
	s_nop 0
	v_add_f32_e32 v110, 1.0, v110
	v_rcp_f32_e32 v110, v110
	s_nop 0
	v_mul_f32_e32 v104, v104, v110
	v_mul_f32_e32 v110, 0x3d372713, v105
	v_mul_f32_e32 v110, v105, v110
	v_fma_f32 v110, v105, v110, v105
	v_mul_f32_e32 v110, 0x3f4c422a, v110
	v_add_f32_e32 v110, v110, v110
	v_mul_f32_e32 v110, 0xbfb8aa3b, v110
	v_exp_f32_e32 v110, v110
	s_nop 0
	v_add_f32_e32 v110, 1.0, v110
	v_rcp_f32_e32 v110, v110
	s_nop 0
	v_mul_f32_e32 v105, v105, v110
	v_cvt_pk_bf16_f32 v110, v104, v105
	v_mul_f32_e32 v104, 0x3d372713, v106
	v_mul_f32_e32 v104, v106, v104
	v_fma_f32 v104, v106, v104, v106
	v_mul_f32_e32 v104, 0x3f4c422a, v104
	v_add_f32_e32 v104, v104, v104
	v_mul_f32_e32 v104, 0xbfb8aa3b, v104
	v_exp_f32_e32 v104, v104
	s_nop 0
	v_add_f32_e32 v104, 1.0, v104
	v_rcp_f32_e32 v104, v104
	s_nop 0
	v_mul_f32_e32 v105, 0x3d372713, v107
	v_mul_f32_e32 v105, v107, v105
	v_fma_f32 v105, v107, v105, v107
	v_mul_f32_e32 v105, 0x3f4c422a, v105
	v_add_f32_e32 v105, v105, v105
	v_mul_f32_e32 v105, 0xbfb8aa3b, v105
	v_exp_f32_e32 v105, v105
	v_mul_f32_e32 v104, v106, v104
	v_add_f32_e32 v105, 1.0, v105
	v_rcp_f32_e32 v105, v105
	s_nop 0
	v_mul_f32_e32 v105, v107, v105
	v_cvt_pk_bf16_f32 v111, v104, v105
	v_lshl_add_u64 v[104:105], s[8:9], 0, v[114:115]
	v_lshl_add_u64 v[106:107], v[104:105], 0, v[120:121]
	v_lshl_add_u64 v[106:107], v[106:107], 0, s[22:23]
	v_lshl_add_u64 v[106:107], v[106:107], 0, v[224:225]
	global_store_dwordx4 v[106:107], v[108:111], off
	v_mul_f32_e32 v106, 0x3d372713, v100
	v_mul_f32_e32 v106, v100, v106
	v_fma_f32 v106, v100, v106, v100
	v_mul_f32_e32 v106, 0x3f4c422a, v106
	v_add_f32_e32 v106, v106, v106
	v_mul_f32_e32 v106, 0xbfb8aa3b, v106
	v_exp_f32_e32 v106, v106
	s_nop 0
	v_add_f32_e32 v106, 1.0, v106
	v_rcp_f32_e32 v106, v106
	s_nop 0
	v_mul_f32_e32 v100, v100, v106
	v_mul_f32_e32 v106, 0x3d372713, v101
	v_mul_f32_e32 v106, v101, v106
	v_fma_f32 v106, v101, v106, v101
	v_mul_f32_e32 v106, 0x3f4c422a, v106
	v_add_f32_e32 v106, v106, v106
	v_mul_f32_e32 v106, 0xbfb8aa3b, v106
	v_exp_f32_e32 v106, v106
	s_nop 0
	v_add_f32_e32 v106, 1.0, v106
	v_rcp_f32_e32 v106, v106
	s_nop 0
	v_mul_f32_e32 v101, v101, v106
	v_cvt_pk_bf16_f32 v100, v100, v101
	v_mul_f32_e32 v101, 0x3d372713, v102
	v_mul_f32_e32 v101, v102, v101
	v_fma_f32 v101, v102, v101, v102
	v_mul_f32_e32 v101, 0x3f4c422a, v101
	v_add_f32_e32 v101, v101, v101
	v_mul_f32_e32 v101, 0xbfb8aa3b, v101
	v_exp_f32_e32 v101, v101
	s_nop 0
	v_add_f32_e32 v101, 1.0, v101
	v_rcp_f32_e32 v101, v101
	s_nop 0
	v_mul_f32_e32 v101, v102, v101
	v_mul_f32_e32 v102, 0x3d372713, v103
	v_mul_f32_e32 v102, v103, v102
	v_fma_f32 v102, v103, v102, v103
	v_mul_f32_e32 v102, 0x3f4c422a, v102
	v_add_f32_e32 v102, v102, v102
	v_mul_f32_e32 v102, 0xbfb8aa3b, v102
	v_exp_f32_e32 v102, v102
; __device__ __forceinline__ unsigned cvt_pk_bf16(float lo, float hi) { unsigned r; asm volatile("v_cvt_pk_bf16_f32 %0, %1, %2" : "=v"(r) : "v"(lo), "v"(hi)); return r; }
; __device__ __forceinline__ float gelu_tanh_f(float y) { const float t = 0.7978845608028654f * (y + 0.044715f * y * y * y); return y * sigmoid_f(2.0f * t); }
; __device__ __forceinline__ float silu_f(float z) { return z / (1.0f + __expf(-z)); }
; __device__ __forceinline__ float sigmoid_f(float z) { return 1.0f / (1.0f + __expf(-z)); }
;     __device__ __forceinline__ void operator()(const AccT& acc, const Unit& u, int wr, int wc, int fr, int fq) const {
;     ...
;                     u32x4 w; w.x = cvt_pk_bf16(gelu_tanh_f(v0[0]), gelu_tanh_f(v0[1])); w.y = cvt_pk_bf16(gelu_tanh_f(v0[2]), gelu_tanh_f(v0[3]));
;                     w.z = cvt_pk_bf16(gelu_tanh_f(v1[0]), gelu_tanh_f(v1[1])); w.w = cvt_pk_bf16(gelu_tanh_f(v1[2]), gelu_tanh_f(v1[3]));
;                     *(u32x4*)(YG + ((size_t)rg * 32 + i) * 1024 + u.g * 16 + s0) = w;
	s_nop 0
	v_add_f32_e32 v102, 1.0, v102
	v_rcp_f32_e32 v102, v102
	s_nop 0
	v_mul_f32_e32 v102, v103, v102
	v_cvt_pk_bf16_f32 v101, v101, v102
	v_mul_f32_e32 v102, 0x3d372713, v96
	v_mul_f32_e32 v102, v96, v102
	v_fma_f32 v102, v96, v102, v96
	v_mul_f32_e32 v102, 0x3f4c422a, v102
	v_add_f32_e32 v102, v102, v102
	v_mul_f32_e32 v102, 0xbfb8aa3b, v102
	v_exp_f32_e32 v102, v102
	s_nop 0
	v_add_f32_e32 v102, 1.0, v102
	v_rcp_f32_e32 v102, v102
	s_nop 0
	v_mul_f32_e32 v96, v96, v102
	v_mul_f32_e32 v102, 0x3d372713, v97
	v_mul_f32_e32 v102, v97, v102
	v_fma_f32 v102, v97, v102, v97
	v_mul_f32_e32 v102, 0x3f4c422a, v102
	v_add_f32_e32 v102, v102, v102
	v_mul_f32_e32 v102, 0xbfb8aa3b, v102
	v_exp_f32_e32 v102, v102
	s_nop 0
	v_add_f32_e32 v102, 1.0, v102
	v_rcp_f32_e32 v102, v102
	s_nop 0
	v_mul_f32_e32 v97, v97, v102
	v_cvt_pk_bf16_f32 v102, v96, v97
	v_mul_f32_e32 v96, 0x3d372713, v98
	v_mul_f32_e32 v96, v98, v96
	v_fma_f32 v96, v98, v96, v98
	v_mul_f32_e32 v96, 0x3f4c422a, v96
	v_add_f32_e32 v96, v96, v96
	v_mul_f32_e32 v96, 0xbfb8aa3b, v96
	v_exp_f32_e32 v96, v96
	s_nop 0
	v_add_f32_e32 v96, 1.0, v96
	v_rcp_f32_e32 v96, v96
	s_nop 0
	v_mul_f32_e32 v97, 0x3d372713, v99
	v_mul_f32_e32 v97, v99, v97
	v_fma_f32 v97, v99, v97, v99
	v_mul_f32_e32 v97, 0x3f4c422a, v97
	v_add_f32_e32 v97, v97, v97
	v_mul_f32_e32 v97, 0xbfb8aa3b, v97
	v_exp_f32_e32 v97, v97
	v_mul_f32_e32 v96, v98, v96
	v_add_f32_e32 v97, 1.0, v97
	v_rcp_f32_e32 v97, v97
	s_nop 0
	v_mul_f32_e32 v98, 0x3d372713, v92
	v_mul_f32_e32 v98, v92, v98
	v_fma_f32 v98, v92, v98, v92
	v_mul_f32_e32 v98, 0x3f4c422a, v98
	v_add_f32_e32 v98, v98, v98
	v_mul_f32_e32 v98, 0xbfb8aa3b, v98
	v_exp_f32_e32 v98, v98
	v_mul_f32_e32 v97, v99, v97
	v_cvt_pk_bf16_f32 v103, v96, v97
	v_lshl_add_u64 v[96:97], v[104:105], 0, v[112:113]
	v_lshl_add_u64 v[96:97], v[96:97], 0, s[22:23]
	v_add_f32_e32 v98, 1.0, v98
	v_lshl_add_u64 v[96:97], v[96:97], 0, v[224:225]
	global_store_dwordx4 v[96:97], v[100:103], off
	v_add_u32_e32 v96, s24, v147
	v_ashrrev_i32_e32 v97, 31, v96
	v_lshlrev_b64 v[96:97], 16, v[96:97]
	v_rcp_f32_e32 v98, v98
	s_nop 0
	v_mul_f32_e32 v92, v92, v98
	v_mul_f32_e32 v98, 0x3d372713, v93
	v_mul_f32_e32 v98, v93, v98
	v_fma_f32 v98, v93, v98, v93
	v_mul_f32_e32 v98, 0x3f4c422a, v98
	v_add_f32_e32 v98, v98, v98
	v_mul_f32_e32 v98, 0xbfb8aa3b, v98
	v_exp_f32_e32 v98, v98
	s_nop 0
	v_add_f32_e32 v98, 1.0, v98
	v_rcp_f32_e32 v98, v98
	s_nop 0
	v_mul_f32_e32 v93, v93, v98
	v_cvt_pk_bf16_f32 v92, v92, v93
	v_mul_f32_e32 v93, 0x3d372713, v94
	v_mul_f32_e32 v93, v94, v93
	v_fma_f32 v93, v94, v93, v94
	v_mul_f32_e32 v93, 0x3f4c422a, v93
	v_add_f32_e32 v93, v93, v93
	v_mul_f32_e32 v93, 0xbfb8aa3b, v93
	v_exp_f32_e32 v93, v93
	s_nop 0
	v_add_f32_e32 v93, 1.0, v93
	v_rcp_f32_e32 v93, v93
	s_nop 0
	v_mul_f32_e32 v93, v94, v93
	v_mul_f32_e32 v94, 0x3d372713, v95
	v_mul_f32_e32 v94, v95, v94
	v_fma_f32 v94, v95, v94, v95
	v_mul_f32_e32 v94, 0x3f4c422a, v94
	v_add_f32_e32 v94, v94, v94
	v_mul_f32_e32 v94, 0xbfb8aa3b, v94
	v_exp_f32_e32 v94, v94
	s_nop 0
	v_add_f32_e32 v94, 1.0, v94
	v_rcp_f32_e32 v94, v94
	s_nop 0
	v_mul_f32_e32 v94, v95, v94
	v_cvt_pk_bf16_f32 v93, v93, v94
	v_mul_f32_e32 v94, 0x3d372713, v88
	v_mul_f32_e32 v94, v88, v94
	v_fma_f32 v94, v88, v94, v88
	v_mul_f32_e32 v94, 0x3f4c422a, v94
	v_add_f32_e32 v94, v94, v94
	v_mul_f32_e32 v94, 0xbfb8aa3b, v94
	v_exp_f32_e32 v94, v94
	s_nop 0
	v_add_f32_e32 v94, 1.0, v94
	v_rcp_f32_e32 v94, v94
	s_nop 0
	v_mul_f32_e32 v88, v88, v94
	v_mul_f32_e32 v94, 0x3d372713, v89
	v_mul_f32_e32 v94, v89, v94
	v_fma_f32 v94, v89, v94, v89
	v_mul_f32_e32 v94, 0x3f4c422a, v94
	v_add_f32_e32 v94, v94, v94
	v_mul_f32_e32 v94, 0xbfb8aa3b, v94
	v_exp_f32_e32 v94, v94
	s_nop 0
	v_add_f32_e32 v94, 1.0, v94
	v_rcp_f32_e32 v94, v94
	s_nop 0
	v_mul_f32_e32 v89, v89, v94
	v_cvt_pk_bf16_f32 v94, v88, v89
	v_mul_f32_e32 v88, 0x3d372713, v90
	v_mul_f32_e32 v88, v90, v88
	v_fma_f32 v88, v90, v88, v90
	v_mul_f32_e32 v88, 0x3f4c422a, v88
	v_add_f32_e32 v88, v88, v88
	v_mul_f32_e32 v88, 0xbfb8aa3b, v88
	v_exp_f32_e32 v88, v88
	s_nop 0
	v_add_f32_e32 v88, 1.0, v88
	v_rcp_f32_e32 v88, v88
	s_nop 0
	v_mul_f32_e32 v89, 0x3d372713, v91
	v_mul_f32_e32 v89, v91, v89
	v_fma_f32 v89, v91, v89, v91
	v_mul_f32_e32 v89, 0x3f4c422a, v89
	v_add_f32_e32 v89, v89, v89
	v_mul_f32_e32 v89, 0xbfb8aa3b, v89
	v_exp_f32_e32 v89, v89
	v_mul_f32_e32 v88, v90, v88
	v_add_f32_e32 v89, 1.0, v89
	v_rcp_f32_e32 v89, v89
	s_nop 0
	v_mul_f32_e32 v89, v91, v89
	v_cvt_pk_bf16_f32 v95, v88, v89
	v_lshl_add_u64 v[88:89], s[8:9], 0, v[96:97]
	v_lshl_add_u64 v[90:91], v[88:89], 0, v[120:121]
	v_lshl_add_u64 v[90:91], v[90:91], 0, s[22:23]
	v_lshl_add_u64 v[90:91], v[90:91], 0, v[224:225]
	global_store_dwordx4 v[90:91], v[92:95], off
	v_mul_f32_e32 v90, 0x3d372713, v84
	v_mul_f32_e32 v90, v84, v90
	v_fma_f32 v90, v84, v90, v84
	v_mul_f32_e32 v90, 0x3f4c422a, v90
	v_add_f32_e32 v90, v90, v90
	v_mul_f32_e32 v90, 0xbfb8aa3b, v90
	v_exp_f32_e32 v90, v90
	s_nop 0
	v_add_f32_e32 v90, 1.0, v90
	v_rcp_f32_e32 v90, v90
	s_nop 0
	v_mul_f32_e32 v84, v84, v90
	v_mul_f32_e32 v90, 0x3d372713, v85
	v_mul_f32_e32 v90, v85, v90
	v_fma_f32 v90, v85, v90, v85
	v_mul_f32_e32 v90, 0x3f4c422a, v90
	v_add_f32_e32 v90, v90, v90
	v_mul_f32_e32 v90, 0xbfb8aa3b, v90
	v_exp_f32_e32 v90, v90
	s_nop 0
	v_add_f32_e32 v90, 1.0, v90
	v_rcp_f32_e32 v90, v90
	s_nop 0
	v_mul_f32_e32 v85, v85, v90
	v_cvt_pk_bf16_f32 v84, v84, v85
	v_mul_f32_e32 v85, 0x3d372713, v86
	v_mul_f32_e32 v85, v86, v85
	v_fma_f32 v85, v86, v85, v86
	v_mul_f32_e32 v85, 0x3f4c422a, v85
	v_add_f32_e32 v85, v85, v85
	v_mul_f32_e32 v85, 0xbfb8aa3b, v85
	v_exp_f32_e32 v85, v85
	s_nop 0
; __device__ __forceinline__ unsigned cvt_pk_bf16(float lo, float hi) { unsigned r; asm volatile("v_cvt_pk_bf16_f32 %0, %1, %2" : "=v"(r) : "v"(lo), "v"(hi)); return r; }
; __device__ __forceinline__ float gelu_tanh_f(float y) { const float t = 0.7978845608028654f * (y + 0.044715f * y * y * y); return y * sigmoid_f(2.0f * t); }
; __device__ __forceinline__ float silu_f(float z) { return z / (1.0f + __expf(-z)); }
; __device__ __forceinline__ float sigmoid_f(float z) { return 1.0f / (1.0f + __expf(-z)); }
;     __device__ __forceinline__ void operator()(const AccT& acc, const Unit& u, int wr, int wc, int fr, int fq) const {
;     ...
;                     u32x4 w; w.x = cvt_pk_bf16(gelu_tanh_f(v0[0]), gelu_tanh_f(v0[1])); w.y = cvt_pk_bf16(gelu_tanh_f(v0[2]), gelu_tanh_f(v0[3]));
;                     w.z = cvt_pk_bf16(gelu_tanh_f(v1[0]), gelu_tanh_f(v1[1])); w.w = cvt_pk_bf16(gelu_tanh_f(v1[2]), gelu_tanh_f(v1[3]));
;                     *(u32x4*)(YG + ((size_t)rg * 32 + i) * 1024 + u.g * 16 + s0) = w;
	v_add_f32_e32 v85, 1.0, v85
	v_rcp_f32_e32 v85, v85
	s_nop 0
	v_mul_f32_e32 v85, v86, v85
	v_mul_f32_e32 v86, 0x3d372713, v87
	v_mul_f32_e32 v86, v87, v86
	v_fma_f32 v86, v87, v86, v87
	v_mul_f32_e32 v86, 0x3f4c422a, v86
	v_add_f32_e32 v86, v86, v86
	v_mul_f32_e32 v86, 0xbfb8aa3b, v86
	v_exp_f32_e32 v86, v86
	s_nop 0
	v_add_f32_e32 v86, 1.0, v86
	v_rcp_f32_e32 v86, v86
	s_nop 0
	v_mul_f32_e32 v86, v87, v86
	v_cvt_pk_bf16_f32 v85, v85, v86
	v_mul_f32_e32 v86, 0x3d372713, v80
	v_mul_f32_e32 v86, v80, v86
	v_fma_f32 v86, v80, v86, v80
	v_mul_f32_e32 v86, 0x3f4c422a, v86
	v_add_f32_e32 v86, v86, v86
	v_mul_f32_e32 v86, 0xbfb8aa3b, v86
	v_exp_f32_e32 v86, v86
	s_nop 0
	v_add_f32_e32 v86, 1.0, v86
	v_rcp_f32_e32 v86, v86
	s_nop 0
	v_mul_f32_e32 v80, v80, v86
	v_mul_f32_e32 v86, 0x3d372713, v81
	v_mul_f32_e32 v86, v81, v86
	v_fma_f32 v86, v81, v86, v81
	v_mul_f32_e32 v86, 0x3f4c422a, v86
	v_add_f32_e32 v86, v86, v86
	v_mul_f32_e32 v86, 0xbfb8aa3b, v86
	v_exp_f32_e32 v86, v86
	s_nop 0
	v_add_f32_e32 v86, 1.0, v86
	v_rcp_f32_e32 v86, v86
	s_nop 0
	v_mul_f32_e32 v81, v81, v86
	v_cvt_pk_bf16_f32 v86, v80, v81
	v_mul_f32_e32 v80, 0x3d372713, v82
	v_mul_f32_e32 v80, v82, v80
	v_fma_f32 v80, v82, v80, v82
	v_mul_f32_e32 v80, 0x3f4c422a, v80
	v_add_f32_e32 v80, v80, v80
	v_mul_f32_e32 v80, 0xbfb8aa3b, v80
	v_exp_f32_e32 v80, v80
	s_nop 0
	v_add_f32_e32 v80, 1.0, v80
	v_rcp_f32_e32 v80, v80
	s_nop 0
	v_mul_f32_e32 v81, 0x3d372713, v83
	v_mul_f32_e32 v81, v83, v81
	v_fma_f32 v81, v83, v81, v83
	v_mul_f32_e32 v81, 0x3f4c422a, v81
	v_add_f32_e32 v81, v81, v81
	v_mul_f32_e32 v81, 0xbfb8aa3b, v81
	v_exp_f32_e32 v81, v81
	v_mul_f32_e32 v80, v82, v80
	v_add_f32_e32 v81, 1.0, v81
	v_rcp_f32_e32 v81, v81
	s_nop 0
	v_mul_f32_e32 v82, 0x3d372713, v76
	v_mul_f32_e32 v82, v76, v82
	v_fma_f32 v82, v76, v82, v76
	v_mul_f32_e32 v82, 0x3f4c422a, v82
	v_add_f32_e32 v82, v82, v82
	v_mul_f32_e32 v82, 0xbfb8aa3b, v82
	v_exp_f32_e32 v82, v82
	v_mul_f32_e32 v81, v83, v81
	v_cvt_pk_bf16_f32 v87, v80, v81
	v_lshl_add_u64 v[80:81], v[88:89], 0, v[112:113]
	v_lshl_add_u64 v[80:81], v[80:81], 0, s[22:23]
	v_add_f32_e32 v82, 1.0, v82
	v_lshl_add_u64 v[80:81], v[80:81], 0, v[224:225]
	global_store_dwordx4 v[80:81], v[84:87], off
	v_add_u32_e32 v80, s24, v148
	v_ashrrev_i32_e32 v81, 31, v80
	v_lshlrev_b64 v[80:81], 16, v[80:81]
	v_rcp_f32_e32 v82, v82
	s_nop 0
	v_mul_f32_e32 v76, v76, v82
	v_mul_f32_e32 v82, 0x3d372713, v77
	v_mul_f32_e32 v82, v77, v82
	v_fma_f32 v82, v77, v82, v77
	v_mul_f32_e32 v82, 0x3f4c422a, v82
	v_add_f32_e32 v82, v82, v82
	v_mul_f32_e32 v82, 0xbfb8aa3b, v82
	v_exp_f32_e32 v82, v82
	s_nop 0
	v_add_f32_e32 v82, 1.0, v82
	v_rcp_f32_e32 v82, v82
	s_nop 0
	v_mul_f32_e32 v77, v77, v82
	v_cvt_pk_bf16_f32 v76, v76, v77
	v_mul_f32_e32 v77, 0x3d372713, v78
	v_mul_f32_e32 v77, v78, v77
	v_fma_f32 v77, v78, v77, v78
	v_mul_f32_e32 v77, 0x3f4c422a, v77
	v_add_f32_e32 v77, v77, v77
	v_mul_f32_e32 v77, 0xbfb8aa3b, v77
	v_exp_f32_e32 v77, v77
	s_nop 0
	v_add_f32_e32 v77, 1.0, v77
	v_rcp_f32_e32 v77, v77
	s_nop 0
	v_mul_f32_e32 v77, v78, v77
	v_mul_f32_e32 v78, 0x3d372713, v79
	v_mul_f32_e32 v78, v79, v78
	v_fma_f32 v78, v79, v78, v79
	v_mul_f32_e32 v78, 0x3f4c422a, v78
	v_add_f32_e32 v78, v78, v78
	v_mul_f32_e32 v78, 0xbfb8aa3b, v78
	v_exp_f32_e32 v78, v78
	s_nop 0
	v_add_f32_e32 v78, 1.0, v78
	v_rcp_f32_e32 v78, v78
	s_nop 0
	v_mul_f32_e32 v78, v79, v78
	v_cvt_pk_bf16_f32 v77, v77, v78
	v_mul_f32_e32 v78, 0x3d372713, v72
	v_mul_f32_e32 v78, v72, v78
	v_fma_f32 v78, v72, v78, v72
	v_mul_f32_e32 v78, 0x3f4c422a, v78
	v_add_f32_e32 v78, v78, v78
	v_mul_f32_e32 v78, 0xbfb8aa3b, v78
	v_exp_f32_e32 v78, v78
	s_nop 0
	v_add_f32_e32 v78, 1.0, v78
	v_rcp_f32_e32 v78, v78
	s_nop 0
	v_mul_f32_e32 v72, v72, v78
	v_mul_f32_e32 v78, 0x3d372713, v73
	v_mul_f32_e32 v78, v73, v78
	v_fma_f32 v78, v73, v78, v73
	v_mul_f32_e32 v78, 0x3f4c422a, v78
	v_add_f32_e32 v78, v78, v78
	v_mul_f32_e32 v78, 0xbfb8aa3b, v78
	v_exp_f32_e32 v78, v78
	s_nop 0
	v_add_f32_e32 v78, 1.0, v78
	v_rcp_f32_e32 v78, v78
	s_nop 0
	v_mul_f32_e32 v73, v73, v78
	v_cvt_pk_bf16_f32 v78, v72, v73
	v_mul_f32_e32 v72, 0x3d372713, v74
	v_mul_f32_e32 v72, v74, v72
	v_fma_f32 v72, v74, v72, v74
	v_mul_f32_e32 v72, 0x3f4c422a, v72
	v_add_f32_e32 v72, v72, v72
	v_mul_f32_e32 v72, 0xbfb8aa3b, v72
	v_exp_f32_e32 v72, v72
	s_nop 0
	v_add_f32_e32 v72, 1.0, v72
	v_rcp_f32_e32 v72, v72
	s_nop 0
	v_mul_f32_e32 v73, 0x3d372713, v75
	v_mul_f32_e32 v73, v75, v73
	v_fma_f32 v73, v75, v73, v75
	v_mul_f32_e32 v73, 0x3f4c422a, v73
	v_add_f32_e32 v73, v73, v73
	v_mul_f32_e32 v73, 0xbfb8aa3b, v73
	v_exp_f32_e32 v73, v73
	v_mul_f32_e32 v72, v74, v72
	v_add_f32_e32 v73, 1.0, v73
	v_rcp_f32_e32 v73, v73
	s_nop 0
	v_mul_f32_e32 v73, v75, v73
	v_cvt_pk_bf16_f32 v79, v72, v73
	v_lshl_add_u64 v[72:73], s[8:9], 0, v[80:81]
	v_lshl_add_u64 v[74:75], v[72:73], 0, v[120:121]
	v_lshl_add_u64 v[74:75], v[74:75], 0, s[22:23]
	v_lshl_add_u64 v[74:75], v[74:75], 0, v[224:225]
	global_store_dwordx4 v[74:75], v[76:79], off
	v_mul_f32_e32 v74, 0x3d372713, v68
	v_mul_f32_e32 v74, v68, v74
	v_fma_f32 v74, v68, v74, v68
	v_mul_f32_e32 v74, 0x3f4c422a, v74
	v_add_f32_e32 v74, v74, v74
	v_mul_f32_e32 v74, 0xbfb8aa3b, v74
	v_exp_f32_e32 v74, v74
	s_nop 0
	v_add_f32_e32 v74, 1.0, v74
	v_rcp_f32_e32 v74, v74
	s_nop 0
	v_mul_f32_e32 v68, v68, v74
	v_mul_f32_e32 v74, 0x3d372713, v69
	v_mul_f32_e32 v74, v69, v74
	v_fma_f32 v74, v69, v74, v69
	v_mul_f32_e32 v74, 0x3f4c422a, v74
	v_add_f32_e32 v74, v74, v74
	v_mul_f32_e32 v74, 0xbfb8aa3b, v74
	v_exp_f32_e32 v74, v74
	s_nop 0
	v_add_f32_e32 v74, 1.0, v74
	v_rcp_f32_e32 v74, v74
	s_nop 0
	v_mul_f32_e32 v69, v69, v74
; __device__ __forceinline__ unsigned cvt_pk_bf16(float lo, float hi) { unsigned r; asm volatile("v_cvt_pk_bf16_f32 %0, %1, %2" : "=v"(r) : "v"(lo), "v"(hi)); return r; }
; __device__ __forceinline__ float gelu_tanh_f(float y) { const float t = 0.7978845608028654f * (y + 0.044715f * y * y * y); return y * sigmoid_f(2.0f * t); }
; __device__ __forceinline__ float silu_f(float z) { return z / (1.0f + __expf(-z)); }
; __device__ __forceinline__ float sigmoid_f(float z) { return 1.0f / (1.0f + __expf(-z)); }
;     __device__ __forceinline__ void operator()(const AccT& acc, const Unit& u, int wr, int wc, int fr, int fq) const {
;     ...
;                     u32x4 w; w.x = cvt_pk_bf16(gelu_tanh_f(v0[0]), gelu_tanh_f(v0[1])); w.y = cvt_pk_bf16(gelu_tanh_f(v0[2]), gelu_tanh_f(v0[3]));
;                     w.z = cvt_pk_bf16(gelu_tanh_f(v1[0]), gelu_tanh_f(v1[1])); w.w = cvt_pk_bf16(gelu_tanh_f(v1[2]), gelu_tanh_f(v1[3]));
;                     *(u32x4*)(YG + ((size_t)rg * 32 + i) * 1024 + u.g * 16 + s0) = w;
	v_cvt_pk_bf16_f32 v68, v68, v69
	v_mul_f32_e32 v69, 0x3d372713, v70
	v_mul_f32_e32 v69, v70, v69
	v_fma_f32 v69, v70, v69, v70
	v_mul_f32_e32 v69, 0x3f4c422a, v69
	v_add_f32_e32 v69, v69, v69
	v_mul_f32_e32 v69, 0xbfb8aa3b, v69
	v_exp_f32_e32 v69, v69
	s_nop 0
	v_add_f32_e32 v69, 1.0, v69
	v_rcp_f32_e32 v69, v69
	s_nop 0
	v_mul_f32_e32 v69, v70, v69
	v_mul_f32_e32 v70, 0x3d372713, v71
	v_mul_f32_e32 v70, v71, v70
	v_fma_f32 v70, v71, v70, v71
	v_mul_f32_e32 v70, 0x3f4c422a, v70
	v_add_f32_e32 v70, v70, v70
	v_mul_f32_e32 v70, 0xbfb8aa3b, v70
	v_exp_f32_e32 v70, v70
	s_nop 0
	v_add_f32_e32 v70, 1.0, v70
	v_rcp_f32_e32 v70, v70
	s_nop 0
	v_mul_f32_e32 v70, v71, v70
	v_cvt_pk_bf16_f32 v69, v69, v70
	v_mul_f32_e32 v70, 0x3d372713, v64
	v_mul_f32_e32 v70, v64, v70
	v_fma_f32 v70, v64, v70, v64
	v_mul_f32_e32 v70, 0x3f4c422a, v70
	v_add_f32_e32 v70, v70, v70
	v_mul_f32_e32 v70, 0xbfb8aa3b, v70
	v_exp_f32_e32 v70, v70
	s_nop 0
	v_add_f32_e32 v70, 1.0, v70
	v_rcp_f32_e32 v70, v70
	s_nop 0
	v_mul_f32_e32 v64, v64, v70
	v_mul_f32_e32 v70, 0x3d372713, v65
	v_mul_f32_e32 v70, v65, v70
	v_fma_f32 v70, v65, v70, v65
	v_mul_f32_e32 v70, 0x3f4c422a, v70
	v_add_f32_e32 v70, v70, v70
	v_mul_f32_e32 v70, 0xbfb8aa3b, v70
	v_exp_f32_e32 v70, v70
	s_nop 0
	v_add_f32_e32 v70, 1.0, v70
	v_rcp_f32_e32 v70, v70
	s_nop 0
	v_mul_f32_e32 v65, v65, v70
	v_cvt_pk_bf16_f32 v70, v64, v65
	v_mul_f32_e32 v64, 0x3d372713, v66
	v_mul_f32_e32 v64, v66, v64
	v_fma_f32 v64, v66, v64, v66
	v_mul_f32_e32 v64, 0x3f4c422a, v64
	v_add_f32_e32 v64, v64, v64
	v_mul_f32_e32 v64, 0xbfb8aa3b, v64
	v_exp_f32_e32 v64, v64
	s_nop 0
	v_add_f32_e32 v64, 1.0, v64
	v_rcp_f32_e32 v64, v64
	s_nop 0
	v_mul_f32_e32 v65, 0x3d372713, v67
	v_mul_f32_e32 v65, v67, v65
	v_fma_f32 v65, v67, v65, v67
	v_mul_f32_e32 v65, 0x3f4c422a, v65
	v_add_f32_e32 v65, v65, v65
	v_mul_f32_e32 v65, 0xbfb8aa3b, v65
	v_exp_f32_e32 v65, v65
	v_mul_f32_e32 v64, v66, v64
	v_add_f32_e32 v65, 1.0, v65
	v_rcp_f32_e32 v65, v65
	s_nop 0
	v_mul_f32_e32 v66, 0x3d372713, v60
	v_mul_f32_e32 v66, v60, v66
	v_fma_f32 v66, v60, v66, v60
	v_mul_f32_e32 v66, 0x3f4c422a, v66
	v_add_f32_e32 v66, v66, v66
	v_mul_f32_e32 v66, 0xbfb8aa3b, v66
	v_exp_f32_e32 v66, v66
	v_mul_f32_e32 v65, v67, v65
	v_cvt_pk_bf16_f32 v71, v64, v65
	v_lshl_add_u64 v[64:65], v[72:73], 0, v[112:113]
	v_lshl_add_u64 v[64:65], v[64:65], 0, s[22:23]
	v_add_f32_e32 v66, 1.0, v66
	v_lshl_add_u64 v[64:65], v[64:65], 0, v[224:225]
	global_store_dwordx4 v[64:65], v[68:71], off
	v_add_u32_e32 v64, s24, v149
	v_ashrrev_i32_e32 v65, 31, v64
	v_lshlrev_b64 v[64:65], 16, v[64:65]
	v_rcp_f32_e32 v66, v66
	s_nop 0
	v_mul_f32_e32 v60, v60, v66
	v_mul_f32_e32 v66, 0x3d372713, v61
	v_mul_f32_e32 v66, v61, v66
	v_fma_f32 v66, v61, v66, v61
	v_mul_f32_e32 v66, 0x3f4c422a, v66
	v_add_f32_e32 v66, v66, v66
	v_mul_f32_e32 v66, 0xbfb8aa3b, v66
	v_exp_f32_e32 v66, v66
	s_nop 0
	v_add_f32_e32 v66, 1.0, v66
	v_rcp_f32_e32 v66, v66
	s_nop 0
	v_mul_f32_e32 v61, v61, v66
	v_cvt_pk_bf16_f32 v60, v60, v61
	v_mul_f32_e32 v61, 0x3d372713, v62
	v_mul_f32_e32 v61, v62, v61
	v_fma_f32 v61, v62, v61, v62
	v_mul_f32_e32 v61, 0x3f4c422a, v61
	v_add_f32_e32 v61, v61, v61
	v_mul_f32_e32 v61, 0xbfb8aa3b, v61
	v_exp_f32_e32 v61, v61
	s_nop 0
	v_add_f32_e32 v61, 1.0, v61
	v_rcp_f32_e32 v61, v61
	s_nop 0
	v_mul_f32_e32 v61, v62, v61
	v_mul_f32_e32 v62, 0x3d372713, v63
	v_mul_f32_e32 v62, v63, v62
	v_fma_f32 v62, v63, v62, v63
	v_mul_f32_e32 v62, 0x3f4c422a, v62
	v_add_f32_e32 v62, v62, v62
	v_mul_f32_e32 v62, 0xbfb8aa3b, v62
	v_exp_f32_e32 v62, v62
	s_nop 0
	v_add_f32_e32 v62, 1.0, v62
	v_rcp_f32_e32 v62, v62
	s_nop 0
	v_mul_f32_e32 v62, v63, v62
	v_cvt_pk_bf16_f32 v61, v61, v62
	v_mul_f32_e32 v62, 0x3d372713, v56
	v_mul_f32_e32 v62, v56, v62
	v_fma_f32 v62, v56, v62, v56
	v_mul_f32_e32 v62, 0x3f4c422a, v62
	v_add_f32_e32 v62, v62, v62
	v_mul_f32_e32 v62, 0xbfb8aa3b, v62
	v_exp_f32_e32 v62, v62
	s_nop 0
	v_add_f32_e32 v62, 1.0, v62
	v_rcp_f32_e32 v62, v62
	s_nop 0
	v_mul_f32_e32 v56, v56, v62
	v_mul_f32_e32 v62, 0x3d372713, v57
	v_mul_f32_e32 v62, v57, v62
	v_fma_f32 v62, v57, v62, v57
	v_mul_f32_e32 v62, 0x3f4c422a, v62
	v_add_f32_e32 v62, v62, v62
	v_mul_f32_e32 v62, 0xbfb8aa3b, v62
	v_exp_f32_e32 v62, v62
	s_nop 0
	v_add_f32_e32 v62, 1.0, v62
	v_rcp_f32_e32 v62, v62
	s_nop 0
	v_mul_f32_e32 v57, v57, v62
	v_cvt_pk_bf16_f32 v62, v56, v57
	v_mul_f32_e32 v56, 0x3d372713, v58
	v_mul_f32_e32 v56, v58, v56
	v_fma_f32 v56, v58, v56, v58
	v_mul_f32_e32 v56, 0x3f4c422a, v56
	v_add_f32_e32 v56, v56, v56
	v_mul_f32_e32 v56, 0xbfb8aa3b, v56
	v_exp_f32_e32 v56, v56
	s_nop 0
	v_add_f32_e32 v56, 1.0, v56
	v_rcp_f32_e32 v56, v56
	s_nop 0
	v_mul_f32_e32 v57, 0x3d372713, v59
	v_mul_f32_e32 v57, v59, v57
	v_fma_f32 v57, v59, v57, v59
	v_mul_f32_e32 v57, 0x3f4c422a, v57
	v_add_f32_e32 v57, v57, v57
	v_mul_f32_e32 v57, 0xbfb8aa3b, v57
	v_exp_f32_e32 v57, v57
	v_mul_f32_e32 v56, v58, v56
	v_add_f32_e32 v57, 1.0, v57
	v_rcp_f32_e32 v57, v57
	s_nop 0
	v_mul_f32_e32 v57, v59, v57
	v_cvt_pk_bf16_f32 v63, v56, v57
	v_lshl_add_u64 v[56:57], s[8:9], 0, v[64:65]
	v_lshl_add_u64 v[58:59], v[56:57], 0, v[120:121]
	v_lshl_add_u64 v[58:59], v[58:59], 0, s[22:23]
	v_lshl_add_u64 v[58:59], v[58:59], 0, v[224:225]
	global_store_dwordx4 v[58:59], v[60:63], off
	v_mul_f32_e32 v58, 0x3d372713, v52
	v_mul_f32_e32 v58, v52, v58
	v_fma_f32 v58, v52, v58, v52
	v_mul_f32_e32 v58, 0x3f4c422a, v58
	v_add_f32_e32 v58, v58, v58
	v_mul_f32_e32 v58, 0xbfb8aa3b, v58
	v_exp_f32_e32 v58, v58
	s_nop 0
	v_add_f32_e32 v58, 1.0, v58
	v_rcp_f32_e32 v58, v58
	s_nop 0
	v_mul_f32_e32 v52, v52, v58
	v_mul_f32_e32 v58, 0x3d372713, v53
	v_mul_f32_e32 v58, v53, v58
; __device__ __forceinline__ unsigned cvt_pk_bf16(float lo, float hi) { unsigned r; asm volatile("v_cvt_pk_bf16_f32 %0, %1, %2" : "=v"(r) : "v"(lo), "v"(hi)); return r; }
; __device__ __forceinline__ float gelu_tanh_f(float y) { const float t = 0.7978845608028654f * (y + 0.044715f * y * y * y); return y * sigmoid_f(2.0f * t); }
; __device__ __forceinline__ float silu_f(float z) { return z / (1.0f + __expf(-z)); }
; __device__ __forceinline__ float sigmoid_f(float z) { return 1.0f / (1.0f + __expf(-z)); }
;     __device__ __forceinline__ void operator()(const AccT& acc, const Unit& u, int wr, int wc, int fr, int fq) const {
;     ...
;                     u32x4 w; w.x = cvt_pk_bf16(gelu_tanh_f(v0[0]), gelu_tanh_f(v0[1])); w.y = cvt_pk_bf16(gelu_tanh_f(v0[2]), gelu_tanh_f(v0[3]));
;                     w.z = cvt_pk_bf16(gelu_tanh_f(v1[0]), gelu_tanh_f(v1[1])); w.w = cvt_pk_bf16(gelu_tanh_f(v1[2]), gelu_tanh_f(v1[3]));
;                     *(u32x4*)(YG + ((size_t)rg * 32 + i) * 1024 + u.g * 16 + s0) = w;
	v_fma_f32 v58, v53, v58, v53
	v_mul_f32_e32 v58, 0x3f4c422a, v58
	v_add_f32_e32 v58, v58, v58
	v_mul_f32_e32 v58, 0xbfb8aa3b, v58
	v_exp_f32_e32 v58, v58
	s_nop 0
	v_add_f32_e32 v58, 1.0, v58
	v_rcp_f32_e32 v58, v58
	s_nop 0
	v_mul_f32_e32 v53, v53, v58
	v_cvt_pk_bf16_f32 v52, v52, v53
	v_mul_f32_e32 v53, 0x3d372713, v54
	v_mul_f32_e32 v53, v54, v53
	v_fma_f32 v53, v54, v53, v54
	v_mul_f32_e32 v53, 0x3f4c422a, v53
	v_add_f32_e32 v53, v53, v53
	v_mul_f32_e32 v53, 0xbfb8aa3b, v53
	v_exp_f32_e32 v53, v53
	s_nop 0
	v_add_f32_e32 v53, 1.0, v53
	v_rcp_f32_e32 v53, v53
	s_nop 0
	v_mul_f32_e32 v53, v54, v53
	v_mul_f32_e32 v54, 0x3d372713, v55
	v_mul_f32_e32 v54, v55, v54
	v_fma_f32 v54, v55, v54, v55
	v_mul_f32_e32 v54, 0x3f4c422a, v54
	v_add_f32_e32 v54, v54, v54
	v_mul_f32_e32 v54, 0xbfb8aa3b, v54
	v_exp_f32_e32 v54, v54
	s_nop 0
	v_add_f32_e32 v54, 1.0, v54
	v_rcp_f32_e32 v54, v54
	s_nop 0
	v_mul_f32_e32 v54, v55, v54
	v_cvt_pk_bf16_f32 v53, v53, v54
	v_mul_f32_e32 v54, 0x3d372713, v48
	v_mul_f32_e32 v54, v48, v54
	v_fma_f32 v54, v48, v54, v48
	v_mul_f32_e32 v54, 0x3f4c422a, v54
	v_add_f32_e32 v54, v54, v54
	v_mul_f32_e32 v54, 0xbfb8aa3b, v54
	v_exp_f32_e32 v54, v54
	s_nop 0
	v_add_f32_e32 v54, 1.0, v54
	v_rcp_f32_e32 v54, v54
	s_nop 0
	v_mul_f32_e32 v48, v48, v54
	v_mul_f32_e32 v54, 0x3d372713, v49
	v_mul_f32_e32 v54, v49, v54
	v_fma_f32 v54, v49, v54, v49
	v_mul_f32_e32 v54, 0x3f4c422a, v54
	v_add_f32_e32 v54, v54, v54
	v_mul_f32_e32 v54, 0xbfb8aa3b, v54
	v_exp_f32_e32 v54, v54
	s_nop 0
	v_add_f32_e32 v54, 1.0, v54
	v_rcp_f32_e32 v54, v54
	s_nop 0
	v_mul_f32_e32 v49, v49, v54
	v_cvt_pk_bf16_f32 v54, v48, v49
	v_mul_f32_e32 v48, 0x3d372713, v50
	v_mul_f32_e32 v48, v50, v48
	v_fma_f32 v48, v50, v48, v50
	v_mul_f32_e32 v48, 0x3f4c422a, v48
	v_add_f32_e32 v48, v48, v48
	v_mul_f32_e32 v48, 0xbfb8aa3b, v48
	v_exp_f32_e32 v48, v48
	s_nop 0
	v_add_f32_e32 v48, 1.0, v48
	v_rcp_f32_e32 v48, v48
	s_nop 0
	v_mul_f32_e32 v49, 0x3d372713, v51
	v_mul_f32_e32 v49, v51, v49
	v_fma_f32 v49, v51, v49, v51
	v_mul_f32_e32 v49, 0x3f4c422a, v49
	v_add_f32_e32 v49, v49, v49
	v_mul_f32_e32 v49, 0xbfb8aa3b, v49
	v_exp_f32_e32 v49, v49
	v_mul_f32_e32 v48, v50, v48
	v_add_f32_e32 v49, 1.0, v49
	v_rcp_f32_e32 v49, v49
	s_nop 0
	v_mul_f32_e32 v50, 0x3d372713, v44
	v_mul_f32_e32 v50, v44, v50
	v_fma_f32 v50, v44, v50, v44
	v_mul_f32_e32 v50, 0x3f4c422a, v50
	v_add_f32_e32 v50, v50, v50
	v_mul_f32_e32 v50, 0xbfb8aa3b, v50
	v_exp_f32_e32 v50, v50
	v_mul_f32_e32 v49, v51, v49
	v_cvt_pk_bf16_f32 v55, v48, v49
	v_lshl_add_u64 v[48:49], v[56:57], 0, v[112:113]
	v_lshl_add_u64 v[48:49], v[48:49], 0, s[22:23]
	v_add_f32_e32 v50, 1.0, v50
	v_lshl_add_u64 v[48:49], v[48:49], 0, v[224:225]
	global_store_dwordx4 v[48:49], v[52:55], off
	v_add_u32_e32 v48, s24, v150
	v_ashrrev_i32_e32 v49, 31, v48
	v_lshlrev_b64 v[48:49], 16, v[48:49]
	v_rcp_f32_e32 v50, v50
	s_nop 0
	v_mul_f32_e32 v44, v44, v50
	v_mul_f32_e32 v50, 0x3d372713, v45
	v_mul_f32_e32 v50, v45, v50
	v_fma_f32 v50, v45, v50, v45
	v_mul_f32_e32 v50, 0x3f4c422a, v50
	v_add_f32_e32 v50, v50, v50
	v_mul_f32_e32 v50, 0xbfb8aa3b, v50
	v_exp_f32_e32 v50, v50
	s_nop 0
	v_add_f32_e32 v50, 1.0, v50
	v_rcp_f32_e32 v50, v50
	s_nop 0
	v_mul_f32_e32 v45, v45, v50
	v_cvt_pk_bf16_f32 v44, v44, v45
	v_mul_f32_e32 v45, 0x3d372713, v46
	v_mul_f32_e32 v45, v46, v45
	v_fma_f32 v45, v46, v45, v46
	v_mul_f32_e32 v45, 0x3f4c422a, v45
	v_add_f32_e32 v45, v45, v45
	v_mul_f32_e32 v45, 0xbfb8aa3b, v45
	v_exp_f32_e32 v45, v45
	s_nop 0
	v_add_f32_e32 v45, 1.0, v45
	v_rcp_f32_e32 v45, v45
	s_nop 0
	v_mul_f32_e32 v45, v46, v45
	v_mul_f32_e32 v46, 0x3d372713, v47
	v_mul_f32_e32 v46, v47, v46
	v_fma_f32 v46, v47, v46, v47
	v_mul_f32_e32 v46, 0x3f4c422a, v46
	v_add_f32_e32 v46, v46, v46
	v_mul_f32_e32 v46, 0xbfb8aa3b, v46
	v_exp_f32_e32 v46, v46
	s_nop 0
	v_add_f32_e32 v46, 1.0, v46
	v_rcp_f32_e32 v46, v46
	s_nop 0
	v_mul_f32_e32 v46, v47, v46
	v_cvt_pk_bf16_f32 v45, v45, v46
	v_mul_f32_e32 v46, 0x3d372713, v40
	v_mul_f32_e32 v46, v40, v46
	v_fma_f32 v46, v40, v46, v40
	v_mul_f32_e32 v46, 0x3f4c422a, v46
	v_add_f32_e32 v46, v46, v46
	v_mul_f32_e32 v46, 0xbfb8aa3b, v46
	v_exp_f32_e32 v46, v46
	s_nop 0
	v_add_f32_e32 v46, 1.0, v46
	v_rcp_f32_e32 v46, v46
	s_nop 0
	v_mul_f32_e32 v40, v40, v46
	v_mul_f32_e32 v46, 0x3d372713, v41
	v_mul_f32_e32 v46, v41, v46
	v_fma_f32 v46, v41, v46, v41
	v_mul_f32_e32 v46, 0x3f4c422a, v46
	v_add_f32_e32 v46, v46, v46
	v_mul_f32_e32 v46, 0xbfb8aa3b, v46
	v_exp_f32_e32 v46, v46
	s_nop 0
	v_add_f32_e32 v46, 1.0, v46
	v_rcp_f32_e32 v46, v46
	s_nop 0
	v_mul_f32_e32 v41, v41, v46
	v_cvt_pk_bf16_f32 v46, v40, v41
	v_mul_f32_e32 v40, 0x3d372713, v42
	v_mul_f32_e32 v40, v42, v40
	v_fma_f32 v40, v42, v40, v42
	v_mul_f32_e32 v40, 0x3f4c422a, v40
	v_add_f32_e32 v40, v40, v40
	v_mul_f32_e32 v40, 0xbfb8aa3b, v40
	v_exp_f32_e32 v40, v40
	s_nop 0
	v_add_f32_e32 v40, 1.0, v40
	v_rcp_f32_e32 v40, v40
	s_nop 0
	v_mul_f32_e32 v41, 0x3d372713, v43
	v_mul_f32_e32 v41, v43, v41
	v_fma_f32 v41, v43, v41, v43
	v_mul_f32_e32 v41, 0x3f4c422a, v41
	v_add_f32_e32 v41, v41, v41
	v_mul_f32_e32 v41, 0xbfb8aa3b, v41
	v_exp_f32_e32 v41, v41
	v_mul_f32_e32 v40, v42, v40
	v_add_f32_e32 v41, 1.0, v41
	v_rcp_f32_e32 v41, v41
	s_nop 0
	v_mul_f32_e32 v41, v43, v41
	v_cvt_pk_bf16_f32 v47, v40, v41
	v_lshl_add_u64 v[40:41], s[8:9], 0, v[48:49]
	v_lshl_add_u64 v[42:43], v[40:41], 0, v[120:121]
	v_lshl_add_u64 v[42:43], v[42:43], 0, s[22:23]
	v_lshl_add_u64 v[42:43], v[42:43], 0, v[224:225]
	global_store_dwordx4 v[42:43], v[44:47], off
	v_mul_f32_e32 v42, 0x3d372713, v36
	v_mul_f32_e32 v42, v36, v42
	v_fma_f32 v42, v36, v42, v36
	v_mul_f32_e32 v42, 0x3f4c422a, v42
; __device__ __forceinline__ unsigned cvt_pk_bf16(float lo, float hi) { unsigned r; asm volatile("v_cvt_pk_bf16_f32 %0, %1, %2" : "=v"(r) : "v"(lo), "v"(hi)); return r; }
; __device__ __forceinline__ float gelu_tanh_f(float y) { const float t = 0.7978845608028654f * (y + 0.044715f * y * y * y); return y * sigmoid_f(2.0f * t); }
; __device__ __forceinline__ float silu_f(float z) { return z / (1.0f + __expf(-z)); }
; __device__ __forceinline__ float sigmoid_f(float z) { return 1.0f / (1.0f + __expf(-z)); }
;     __device__ __forceinline__ void operator()(const AccT& acc, const Unit& u, int wr, int wc, int fr, int fq) const {
; #pragma unroll
;         for (int ai = 0; ai < 2; ++ai)
; #pragma unroll
;             for (int m = 0; m < 4; ++m) {
;                 const int rg = u.pm * 256 + ai * 128 + wr * 64 + m * 16 + fr;
; #pragma unroll
;                 for (int bj = 0; bj < 2; ++bj) {
;                     const int nc = u.pn * 256 + bj * 128 + wc * 32 + 8 * fq, i = nc >> 4, s0 = nc & 15;
;                     const f32x4 v0 = acc[ai][bj][m][0], v1 = acc[ai][bj][m][1];
;                     u32x4 w; w.x = cvt_pk_bf16(gelu_tanh_f(v0[0]), gelu_tanh_f(v0[1])); w.y = cvt_pk_bf16(gelu_tanh_f(v0[2]), gelu_tanh_f(v0[3]));
;                     w.z = cvt_pk_bf16(gelu_tanh_f(v1[0]), gelu_tanh_f(v1[1])); w.w = cvt_pk_bf16(gelu_tanh_f(v1[2]), gelu_tanh_f(v1[3]));
;                     *(u32x4*)(YG + ((size_t)rg * 32 + i) * 1024 + u.g * 16 + s0) = w;
;                 }
;             }
;     }
	v_add_f32_e32 v42, v42, v42
	v_mul_f32_e32 v42, 0xbfb8aa3b, v42
	v_exp_f32_e32 v42, v42
	s_nop 0
	v_add_f32_e32 v42, 1.0, v42
	v_rcp_f32_e32 v42, v42
	s_nop 0
	v_mul_f32_e32 v36, v36, v42
	v_mul_f32_e32 v42, 0x3d372713, v37
	v_mul_f32_e32 v42, v37, v42
	v_fma_f32 v42, v37, v42, v37
	v_mul_f32_e32 v42, 0x3f4c422a, v42
	v_add_f32_e32 v42, v42, v42
	v_mul_f32_e32 v42, 0xbfb8aa3b, v42
	v_exp_f32_e32 v42, v42
	s_nop 0
	v_add_f32_e32 v42, 1.0, v42
	v_rcp_f32_e32 v42, v42
	s_nop 0
	v_mul_f32_e32 v37, v37, v42
	v_cvt_pk_bf16_f32 v36, v36, v37
	v_mul_f32_e32 v37, 0x3d372713, v38
	v_mul_f32_e32 v37, v38, v37
	v_fma_f32 v37, v38, v37, v38
	v_mul_f32_e32 v37, 0x3f4c422a, v37
	v_add_f32_e32 v37, v37, v37
	v_mul_f32_e32 v37, 0xbfb8aa3b, v37
	v_exp_f32_e32 v37, v37
	s_nop 0
	v_add_f32_e32 v37, 1.0, v37
	v_rcp_f32_e32 v37, v37
	s_nop 0
	v_mul_f32_e32 v37, v38, v37
	v_mul_f32_e32 v38, 0x3d372713, v39
	v_mul_f32_e32 v38, v39, v38
	v_fma_f32 v38, v39, v38, v39
	v_mul_f32_e32 v38, 0x3f4c422a, v38
	v_add_f32_e32 v38, v38, v38
	v_mul_f32_e32 v38, 0xbfb8aa3b, v38
	v_exp_f32_e32 v38, v38
	s_nop 0
	v_add_f32_e32 v38, 1.0, v38
	v_rcp_f32_e32 v38, v38
	s_nop 0
	v_mul_f32_e32 v38, v39, v38
	v_cvt_pk_bf16_f32 v37, v37, v38
	v_mul_f32_e32 v38, 0x3d372713, v32
	v_mul_f32_e32 v38, v32, v38
	v_fma_f32 v38, v32, v38, v32
	v_mul_f32_e32 v38, 0x3f4c422a, v38
	v_add_f32_e32 v38, v38, v38
	v_mul_f32_e32 v38, 0xbfb8aa3b, v38
	v_exp_f32_e32 v38, v38
	s_nop 0
	v_add_f32_e32 v38, 1.0, v38
	v_rcp_f32_e32 v38, v38
	s_nop 0
	v_mul_f32_e32 v32, v32, v38
	v_mul_f32_e32 v38, 0x3d372713, v33
	v_mul_f32_e32 v38, v33, v38
	v_fma_f32 v38, v33, v38, v33
	v_mul_f32_e32 v38, 0x3f4c422a, v38
	v_add_f32_e32 v38, v38, v38
	v_mul_f32_e32 v38, 0xbfb8aa3b, v38
	v_exp_f32_e32 v38, v38
	s_nop 0
	v_add_f32_e32 v38, 1.0, v38
	v_rcp_f32_e32 v38, v38
	s_nop 0
	v_mul_f32_e32 v33, v33, v38
	v_cvt_pk_bf16_f32 v38, v32, v33
	v_mul_f32_e32 v32, 0x3d372713, v34
	v_mul_f32_e32 v32, v34, v32
	v_fma_f32 v32, v34, v32, v34
	v_mul_f32_e32 v32, 0x3f4c422a, v32
	v_add_f32_e32 v32, v32, v32
	v_mul_f32_e32 v32, 0xbfb8aa3b, v32
	v_exp_f32_e32 v32, v32
	s_nop 0
	v_add_f32_e32 v32, 1.0, v32
	v_rcp_f32_e32 v32, v32
	s_nop 0
	v_mul_f32_e32 v33, 0x3d372713, v35
	v_mul_f32_e32 v33, v35, v33
	v_fma_f32 v33, v35, v33, v35
	v_mul_f32_e32 v33, 0x3f4c422a, v33
	v_add_f32_e32 v33, v33, v33
	v_mul_f32_e32 v33, 0xbfb8aa3b, v33
	v_exp_f32_e32 v33, v33
	v_mul_f32_e32 v32, v34, v32
	v_add_f32_e32 v33, 1.0, v33
	v_rcp_f32_e32 v33, v33
	s_nop 0
	v_mul_f32_e32 v34, 0x3d372713, v28
	v_mul_f32_e32 v34, v28, v34
	v_fma_f32 v34, v28, v34, v28
	v_mul_f32_e32 v34, 0x3f4c422a, v34
	v_add_f32_e32 v34, v34, v34
	v_mul_f32_e32 v34, 0xbfb8aa3b, v34
	v_exp_f32_e32 v34, v34
	v_mul_f32_e32 v33, v35, v33
	v_cvt_pk_bf16_f32 v39, v32, v33
	v_lshl_add_u64 v[32:33], v[40:41], 0, v[112:113]
	v_lshl_add_u64 v[32:33], v[32:33], 0, s[22:23]
	v_add_f32_e32 v34, 1.0, v34
	v_lshl_add_u64 v[32:33], v[32:33], 0, v[224:225]
	global_store_dwordx4 v[32:33], v[36:39], off
	v_add_u32_e32 v32, s24, v151
	v_ashrrev_i32_e32 v33, 31, v32
	v_lshlrev_b64 v[32:33], 16, v[32:33]
	v_rcp_f32_e32 v34, v34
	s_nop 0
	v_mul_f32_e32 v28, v28, v34
	v_mul_f32_e32 v34, 0x3d372713, v29
	v_mul_f32_e32 v34, v29, v34
	v_fma_f32 v34, v29, v34, v29
	v_mul_f32_e32 v34, 0x3f4c422a, v34
	v_add_f32_e32 v34, v34, v34
	v_mul_f32_e32 v34, 0xbfb8aa3b, v34
	v_exp_f32_e32 v34, v34
	s_nop 0
	v_add_f32_e32 v34, 1.0, v34
	v_rcp_f32_e32 v34, v34
	s_nop 0
	v_mul_f32_e32 v29, v29, v34
	v_cvt_pk_bf16_f32 v28, v28, v29
	v_mul_f32_e32 v29, 0x3d372713, v30
	v_mul_f32_e32 v29, v30, v29
	v_fma_f32 v29, v30, v29, v30
	v_mul_f32_e32 v29, 0x3f4c422a, v29
	v_add_f32_e32 v29, v29, v29
	v_mul_f32_e32 v29, 0xbfb8aa3b, v29
	v_exp_f32_e32 v29, v29
	s_nop 0
	v_add_f32_e32 v29, 1.0, v29
	v_rcp_f32_e32 v29, v29
	s_nop 0
	v_mul_f32_e32 v29, v30, v29
	v_mul_f32_e32 v30, 0x3d372713, v31
	v_mul_f32_e32 v30, v31, v30
	v_fma_f32 v30, v31, v30, v31
	v_mul_f32_e32 v30, 0x3f4c422a, v30
	v_add_f32_e32 v30, v30, v30
	v_mul_f32_e32 v30, 0xbfb8aa3b, v30
	v_exp_f32_e32 v30, v30
	s_nop 0
	v_add_f32_e32 v30, 1.0, v30
	v_rcp_f32_e32 v30, v30
	s_nop 0
	v_mul_f32_e32 v30, v31, v30
	v_cvt_pk_bf16_f32 v29, v29, v30
	v_mul_f32_e32 v30, 0x3d372713, v24
	v_mul_f32_e32 v30, v24, v30
	v_fma_f32 v30, v24, v30, v24
	v_mul_f32_e32 v30, 0x3f4c422a, v30
	v_add_f32_e32 v30, v30, v30
	v_mul_f32_e32 v30, 0xbfb8aa3b, v30
	v_exp_f32_e32 v30, v30
	s_nop 0
	v_add_f32_e32 v30, 1.0, v30
	v_rcp_f32_e32 v30, v30
	s_nop 0
	v_mul_f32_e32 v24, v24, v30
	v_mul_f32_e32 v30, 0x3d372713, v25
	v_mul_f32_e32 v30, v25, v30
	v_fma_f32 v30, v25, v30, v25
	v_mul_f32_e32 v30, 0x3f4c422a, v30
	v_add_f32_e32 v30, v30, v30
	v_mul_f32_e32 v30, 0xbfb8aa3b, v30
	v_exp_f32_e32 v30, v30
	s_nop 0
	v_add_f32_e32 v30, 1.0, v30
	v_rcp_f32_e32 v30, v30
	s_nop 0
	v_mul_f32_e32 v25, v25, v30
	v_cvt_pk_bf16_f32 v30, v24, v25
	v_mul_f32_e32 v24, 0x3d372713, v26
	v_mul_f32_e32 v24, v26, v24
	v_fma_f32 v24, v26, v24, v26
	v_mul_f32_e32 v24, 0x3f4c422a, v24
	v_add_f32_e32 v24, v24, v24
	v_mul_f32_e32 v24, 0xbfb8aa3b, v24
	v_exp_f32_e32 v24, v24
	s_nop 0
	v_add_f32_e32 v24, 1.0, v24
	v_rcp_f32_e32 v24, v24
	s_nop 0
	v_mul_f32_e32 v25, 0x3d372713, v27
	v_mul_f32_e32 v25, v27, v25
	v_fma_f32 v25, v27, v25, v27
	v_mul_f32_e32 v25, 0x3f4c422a, v25
	v_add_f32_e32 v25, v25, v25
	v_mul_f32_e32 v25, 0xbfb8aa3b, v25
	v_exp_f32_e32 v25, v25
	v_mul_f32_e32 v24, v26, v24
	v_add_f32_e32 v25, 1.0, v25
	v_rcp_f32_e32 v25, v25
	s_nop 0
	v_mul_f32_e32 v25, v27, v25
	v_cvt_pk_bf16_f32 v31, v24, v25
	v_lshl_add_u64 v[24:25], s[8:9], 0, v[32:33]
	v_lshl_add_u64 v[26:27], v[24:25], 0, v[120:121]
; __device__ __forceinline__ unsigned cvt_pk_bf16(float lo, float hi) { unsigned r; asm volatile("v_cvt_pk_bf16_f32 %0, %1, %2" : "=v"(r) : "v"(lo), "v"(hi)); return r; }
; __device__ __forceinline__ float gelu_tanh_f(float y) { const float t = 0.7978845608028654f * (y + 0.044715f * y * y * y); return y * sigmoid_f(2.0f * t); }
; __device__ __forceinline__ float silu_f(float z) { return z / (1.0f + __expf(-z)); }
; __device__ __forceinline__ float sigmoid_f(float z) { return 1.0f / (1.0f + __expf(-z)); }
;     __device__ __forceinline__ void operator()(const AccT& acc, const Unit& u, int wr, int wc, int fr, int fq) const {
; #pragma unroll
;         for (int ai = 0; ai < 2; ++ai)
; #pragma unroll
;             for (int m = 0; m < 4; ++m) {
;                 const int rg = u.pm * 256 + ai * 128 + wr * 64 + m * 16 + fr;
; #pragma unroll
;                 for (int bj = 0; bj < 2; ++bj) {
;                     const int nc = u.pn * 256 + bj * 128 + wc * 32 + 8 * fq, i = nc >> 4, s0 = nc & 15;
;                     const f32x4 v0 = acc[ai][bj][m][0], v1 = acc[ai][bj][m][1];
;                     u32x4 w; w.x = cvt_pk_bf16(gelu_tanh_f(v0[0]), gelu_tanh_f(v0[1])); w.y = cvt_pk_bf16(gelu_tanh_f(v0[2]), gelu_tanh_f(v0[3]));
;                     w.z = cvt_pk_bf16(gelu_tanh_f(v1[0]), gelu_tanh_f(v1[1])); w.w = cvt_pk_bf16(gelu_tanh_f(v1[2]), gelu_tanh_f(v1[3]));
;                     *(u32x4*)(YG + ((size_t)rg * 32 + i) * 1024 + u.g * 16 + s0) = w;
;                 }
;             }
;     }
	v_lshl_add_u64 v[26:27], v[26:27], 0, s[22:23]
	v_lshl_add_u64 v[26:27], v[26:27], 0, v[224:225]
	global_store_dwordx4 v[26:27], v[28:31], off
	v_mul_f32_e32 v26, 0x3d372713, v20
	v_mul_f32_e32 v26, v20, v26
	v_fma_f32 v26, v20, v26, v20
	v_mul_f32_e32 v26, 0x3f4c422a, v26
	v_add_f32_e32 v26, v26, v26
	v_mul_f32_e32 v26, 0xbfb8aa3b, v26
	v_exp_f32_e32 v26, v26
	s_nop 0
	v_add_f32_e32 v26, 1.0, v26
	v_rcp_f32_e32 v26, v26
	s_nop 0
	v_mul_f32_e32 v20, v20, v26
	v_mul_f32_e32 v26, 0x3d372713, v21
	v_mul_f32_e32 v26, v21, v26
	v_fma_f32 v26, v21, v26, v21
	v_mul_f32_e32 v26, 0x3f4c422a, v26
	v_add_f32_e32 v26, v26, v26
	v_mul_f32_e32 v26, 0xbfb8aa3b, v26
	v_exp_f32_e32 v26, v26
	s_nop 0
	v_add_f32_e32 v26, 1.0, v26
	v_rcp_f32_e32 v26, v26
	s_nop 0
	v_mul_f32_e32 v21, v21, v26
	v_cvt_pk_bf16_f32 v20, v20, v21
	v_mul_f32_e32 v21, 0x3d372713, v22
	v_mul_f32_e32 v21, v22, v21
	v_fma_f32 v21, v22, v21, v22
	v_mul_f32_e32 v21, 0x3f4c422a, v21
	v_add_f32_e32 v21, v21, v21
	v_mul_f32_e32 v21, 0xbfb8aa3b, v21
	v_exp_f32_e32 v21, v21
	s_nop 0
	v_add_f32_e32 v21, 1.0, v21
	v_rcp_f32_e32 v21, v21
	s_nop 0
	v_mul_f32_e32 v21, v22, v21
	v_mul_f32_e32 v22, 0x3d372713, v23
	v_mul_f32_e32 v22, v23, v22
	v_fma_f32 v22, v23, v22, v23
	v_mul_f32_e32 v22, 0x3f4c422a, v22
	v_add_f32_e32 v22, v22, v22
	v_mul_f32_e32 v22, 0xbfb8aa3b, v22
	v_exp_f32_e32 v22, v22
	s_nop 0
	v_add_f32_e32 v22, 1.0, v22
	v_rcp_f32_e32 v22, v22
	s_nop 0
	v_mul_f32_e32 v22, v23, v22
	v_cvt_pk_bf16_f32 v21, v21, v22
	v_mul_f32_e32 v22, 0x3d372713, v16
	v_mul_f32_e32 v22, v16, v22
	v_fma_f32 v22, v16, v22, v16
	v_mul_f32_e32 v22, 0x3f4c422a, v22
	v_add_f32_e32 v22, v22, v22
	v_mul_f32_e32 v22, 0xbfb8aa3b, v22
	v_exp_f32_e32 v22, v22
	s_nop 0
	v_add_f32_e32 v22, 1.0, v22
	v_rcp_f32_e32 v22, v22
	s_nop 0
	v_mul_f32_e32 v16, v16, v22
	v_mul_f32_e32 v22, 0x3d372713, v17
	v_mul_f32_e32 v22, v17, v22
	v_fma_f32 v22, v17, v22, v17
	v_mul_f32_e32 v22, 0x3f4c422a, v22
	v_add_f32_e32 v22, v22, v22
	v_mul_f32_e32 v22, 0xbfb8aa3b, v22
	v_exp_f32_e32 v22, v22
	s_nop 0
	v_add_f32_e32 v22, 1.0, v22
	v_rcp_f32_e32 v22, v22
	s_nop 0
	v_mul_f32_e32 v17, v17, v22
	v_cvt_pk_bf16_f32 v22, v16, v17
	v_mul_f32_e32 v16, 0x3d372713, v18
	v_mul_f32_e32 v16, v18, v16
	v_fma_f32 v16, v18, v16, v18
	v_mul_f32_e32 v16, 0x3f4c422a, v16
	v_add_f32_e32 v16, v16, v16
	v_mul_f32_e32 v16, 0xbfb8aa3b, v16
	v_exp_f32_e32 v16, v16
	s_nop 0
	v_add_f32_e32 v16, 1.0, v16
	v_rcp_f32_e32 v16, v16
	s_nop 0
	v_mul_f32_e32 v17, 0x3d372713, v19
	v_mul_f32_e32 v17, v19, v17
	v_fma_f32 v17, v19, v17, v19
	v_mul_f32_e32 v17, 0x3f4c422a, v17
	v_add_f32_e32 v17, v17, v17
	v_mul_f32_e32 v17, 0xbfb8aa3b, v17
	v_exp_f32_e32 v17, v17
	v_mul_f32_e32 v16, v18, v16
	v_add_f32_e32 v17, 1.0, v17
	v_rcp_f32_e32 v17, v17
	s_nop 0
	v_mul_f32_e32 v18, 0x3d372713, v12
	v_mul_f32_e32 v18, v12, v18
	v_fma_f32 v18, v12, v18, v12
	v_mul_f32_e32 v18, 0x3f4c422a, v18
	v_add_f32_e32 v18, v18, v18
	v_mul_f32_e32 v18, 0xbfb8aa3b, v18
	v_exp_f32_e32 v18, v18
	v_mul_f32_e32 v17, v19, v17
	v_cvt_pk_bf16_f32 v23, v16, v17
	v_lshl_add_u64 v[16:17], v[24:25], 0, v[112:113]
	v_lshl_add_u64 v[16:17], v[16:17], 0, s[22:23]
	v_lshl_add_u64 v[16:17], v[16:17], 0, v[224:225]
	v_add_f32_e32 v18, 1.0, v18
	global_store_dwordx4 v[16:17], v[20:23], off
	v_add_u32_e32 v16, s24, v152
	v_ashrrev_i32_e32 v17, 31, v16
	v_lshlrev_b64 v[16:17], 16, v[16:17]
	v_rcp_f32_e32 v18, v18
	s_nop 0
	v_mul_f32_e32 v12, v12, v18
	v_mul_f32_e32 v18, 0x3d372713, v13
	v_mul_f32_e32 v18, v13, v18
	v_fma_f32 v18, v13, v18, v13
	v_mul_f32_e32 v18, 0x3f4c422a, v18
	v_add_f32_e32 v18, v18, v18
	v_mul_f32_e32 v18, 0xbfb8aa3b, v18
	v_exp_f32_e32 v18, v18
	s_nop 0
	v_add_f32_e32 v18, 1.0, v18
	v_rcp_f32_e32 v18, v18
	s_nop 0
	v_mul_f32_e32 v13, v13, v18
	v_cvt_pk_bf16_f32 v12, v12, v13
	v_mul_f32_e32 v13, 0x3d372713, v14
	v_mul_f32_e32 v13, v14, v13
	v_fma_f32 v13, v14, v13, v14
	v_mul_f32_e32 v13, 0x3f4c422a, v13
	v_add_f32_e32 v13, v13, v13
	v_mul_f32_e32 v13, 0xbfb8aa3b, v13
	v_exp_f32_e32 v13, v13
	s_nop 0
	v_add_f32_e32 v13, 1.0, v13
	v_rcp_f32_e32 v13, v13
	s_nop 0
	v_mul_f32_e32 v13, v14, v13
	v_mul_f32_e32 v14, 0x3d372713, v15
	v_mul_f32_e32 v14, v15, v14
	v_fma_f32 v14, v15, v14, v15
	v_mul_f32_e32 v14, 0x3f4c422a, v14
	v_add_f32_e32 v14, v14, v14
	v_mul_f32_e32 v14, 0xbfb8aa3b, v14
	v_exp_f32_e32 v14, v14
	s_nop 0
	v_add_f32_e32 v14, 1.0, v14
	v_rcp_f32_e32 v14, v14
	s_nop 0
	v_mul_f32_e32 v14, v15, v14
; __device__ __forceinline__ unsigned cvt_pk_bf16(float lo, float hi) { unsigned r; asm volatile("v_cvt_pk_bf16_f32 %0, %1, %2" : "=v"(r) : "v"(lo), "v"(hi)); return r; }
; __device__ __forceinline__ float gelu_tanh_f(float y) { const float t = 0.7978845608028654f * (y + 0.044715f * y * y * y); return y * sigmoid_f(2.0f * t); }
; #define PG8_BAR __builtin_amdgcn_s_barrier()
; template <bool SP2 = true, class Epi, class Sched>
; __device__ __forceinline__ void gemm_phase(LAS unsigned char* lds, const int K, const int lda, const int ldb, const Sched& S, const Epi& E) {
;     ...
;         if constexpr (Epi::FUSED) E.fused(acc, cur, wr, wc, fr, fq, lds, tid); else E(acc, cur, wr, wc, fr, fq);
;         if (!has_next) break;
; #pragma unroll
;         for (int a = 0; a < 2; ++a)
; #pragma unroll
;             for (int b = 0; b < 2; ++b)
; #pragma unroll
;                 for (int m = 0; m < 4; ++m)
; #pragma unroll
;                     for (int n = 0; n < 2; ++n) acc[a][b][m][n] = (f32x4){0.f, 0.f, 0.f, 0.f};
;         cur = nxt; cA = nA; cB = nB; ++ui;
;         if (wr == 1) PG8_BAR;
;     __device__ __forceinline__ void operator()(const AccT& acc, const Unit& u, int wr, int wc, int fr, int fq) const {
; #pragma unroll
;         for (int ai = 0; ai < 2; ++ai)
; #pragma unroll
;             for (int m = 0; m < 4; ++m) {
;                 const int rg = u.pm * 256 + ai * 128 + wr * 64 + m * 16 + fr;
; #pragma unroll
;                 for (int bj = 0; bj < 2; ++bj) {
;                     const int nc = u.pn * 256 + bj * 128 + wc * 32 + 8 * fq, i = nc >> 4, s0 = nc & 15;
;                     const f32x4 v0 = acc[ai][bj][m][0], v1 = acc[ai][bj][m][1];
;                     u32x4 w; w.x = cvt_pk_bf16(gelu_tanh_f(v0[0]), gelu_tanh_f(v0[1])); w.y = cvt_pk_bf16(gelu_tanh_f(v0[2]), gelu_tanh_f(v0[3]));
;                     w.z = cvt_pk_bf16(gelu_tanh_f(v1[0]), gelu_tanh_f(v1[1])); w.w = cvt_pk_bf16(gelu_tanh_f(v1[2]), gelu_tanh_f(v1[3]));
;                     *(u32x4*)(YG + ((size_t)rg * 32 + i) * 1024 + u.g * 16 + s0) = w;
;                 }
;             }
;     }
	v_cvt_pk_bf16_f32 v13, v13, v14
	v_mul_f32_e32 v14, 0x3d372713, v8
	v_mul_f32_e32 v14, v8, v14
	v_fma_f32 v14, v8, v14, v8
	v_mul_f32_e32 v14, 0x3f4c422a, v14
	v_add_f32_e32 v14, v14, v14
	v_mul_f32_e32 v14, 0xbfb8aa3b, v14
	v_exp_f32_e32 v14, v14
	s_nop 0
	v_add_f32_e32 v14, 1.0, v14
	v_rcp_f32_e32 v14, v14
	s_nop 0
	v_mul_f32_e32 v8, v8, v14
	v_mul_f32_e32 v14, 0x3d372713, v9
	v_mul_f32_e32 v14, v9, v14
	v_fma_f32 v14, v9, v14, v9
	v_mul_f32_e32 v14, 0x3f4c422a, v14
	v_add_f32_e32 v14, v14, v14
	v_mul_f32_e32 v14, 0xbfb8aa3b, v14
	v_exp_f32_e32 v14, v14
	s_nop 0
	v_add_f32_e32 v14, 1.0, v14
	v_rcp_f32_e32 v14, v14
	s_nop 0
	v_mul_f32_e32 v9, v9, v14
	v_cvt_pk_bf16_f32 v14, v8, v9
	v_mul_f32_e32 v8, 0x3d372713, v10
	v_mul_f32_e32 v8, v10, v8
	v_fma_f32 v8, v10, v8, v10
	v_mul_f32_e32 v8, 0x3f4c422a, v8
	v_add_f32_e32 v8, v8, v8
	v_mul_f32_e32 v8, 0xbfb8aa3b, v8
	v_exp_f32_e32 v8, v8
	s_nop 0
	v_add_f32_e32 v8, 1.0, v8
	v_rcp_f32_e32 v8, v8
	s_nop 0
	v_mul_f32_e32 v9, 0x3d372713, v11
	v_mul_f32_e32 v9, v11, v9
	v_fma_f32 v9, v11, v9, v11
	v_mul_f32_e32 v9, 0x3f4c422a, v9
	v_add_f32_e32 v9, v9, v9
	v_mul_f32_e32 v9, 0xbfb8aa3b, v9
	v_exp_f32_e32 v9, v9
	v_mul_f32_e32 v8, v10, v8
	v_add_f32_e32 v9, 1.0, v9
	v_rcp_f32_e32 v9, v9
	s_nop 0
	v_mul_f32_e32 v9, v11, v9
	v_cvt_pk_bf16_f32 v15, v8, v9
	v_lshl_add_u64 v[8:9], s[8:9], 0, v[16:17]
	v_lshl_add_u64 v[10:11], v[8:9], 0, v[120:121]
	v_lshl_add_u64 v[10:11], v[10:11], 0, s[22:23]
	v_lshl_add_u64 v[10:11], v[10:11], 0, v[224:225]
	global_store_dwordx4 v[10:11], v[12:15], off
	v_mul_f32_e32 v10, 0x3d372713, v4
	v_mul_f32_e32 v10, v4, v10
	v_fma_f32 v10, v4, v10, v4
	v_mul_f32_e32 v10, 0x3f4c422a, v10
	v_add_f32_e32 v10, v10, v10
	v_mul_f32_e32 v10, 0xbfb8aa3b, v10
	v_exp_f32_e32 v10, v10
	s_nop 0
	v_add_f32_e32 v10, 1.0, v10
	v_rcp_f32_e32 v10, v10
	s_nop 0
	v_mul_f32_e32 v4, v4, v10
	v_mul_f32_e32 v10, 0x3d372713, v5
	v_mul_f32_e32 v10, v5, v10
	v_fma_f32 v10, v5, v10, v5
	v_mul_f32_e32 v10, 0x3f4c422a, v10
	v_add_f32_e32 v10, v10, v10
	v_mul_f32_e32 v10, 0xbfb8aa3b, v10
	v_exp_f32_e32 v10, v10
	s_nop 0
	v_add_f32_e32 v10, 1.0, v10
	v_rcp_f32_e32 v10, v10
	s_nop 0
	v_mul_f32_e32 v5, v5, v10
	v_cvt_pk_bf16_f32 v4, v4, v5
	v_mul_f32_e32 v5, 0x3d372713, v6
	v_mul_f32_e32 v5, v6, v5
	v_fma_f32 v5, v6, v5, v6
	v_mul_f32_e32 v5, 0x3f4c422a, v5
	v_add_f32_e32 v5, v5, v5
	v_mul_f32_e32 v5, 0xbfb8aa3b, v5
	v_exp_f32_e32 v5, v5
	s_nop 0
	v_add_f32_e32 v5, 1.0, v5
	v_rcp_f32_e32 v5, v5
	s_nop 0
	v_mul_f32_e32 v5, v6, v5
	v_mul_f32_e32 v6, 0x3d372713, v7
	v_mul_f32_e32 v6, v7, v6
	v_fma_f32 v6, v7, v6, v7
	v_mul_f32_e32 v6, 0x3f4c422a, v6
	v_add_f32_e32 v6, v6, v6
	v_mul_f32_e32 v6, 0xbfb8aa3b, v6
	v_exp_f32_e32 v6, v6
	s_nop 0
	v_add_f32_e32 v6, 1.0, v6
	v_rcp_f32_e32 v6, v6
	s_nop 0
	v_mul_f32_e32 v6, v7, v6
	v_cvt_pk_bf16_f32 v5, v5, v6
	v_mul_f32_e32 v6, 0x3d372713, v0
	v_mul_f32_e32 v6, v0, v6
	v_fma_f32 v6, v0, v6, v0
	v_mul_f32_e32 v6, 0x3f4c422a, v6
	v_add_f32_e32 v6, v6, v6
	v_mul_f32_e32 v6, 0xbfb8aa3b, v6
	v_exp_f32_e32 v6, v6
	s_nop 0
	v_add_f32_e32 v6, 1.0, v6
	v_rcp_f32_e32 v6, v6
	s_nop 0
	v_mul_f32_e32 v0, v0, v6
	v_mul_f32_e32 v6, 0x3d372713, v1
	v_mul_f32_e32 v6, v1, v6
	v_fma_f32 v6, v1, v6, v1
	v_mul_f32_e32 v6, 0x3f4c422a, v6
	v_add_f32_e32 v6, v6, v6
	v_mul_f32_e32 v6, 0xbfb8aa3b, v6
	v_exp_f32_e32 v6, v6
	s_nop 0
	v_add_f32_e32 v6, 1.0, v6
	v_rcp_f32_e32 v6, v6
	s_nop 0
	v_mul_f32_e32 v1, v1, v6
	v_cvt_pk_bf16_f32 v6, v0, v1
	v_mul_f32_e32 v0, 0x3d372713, v2
	v_mul_f32_e32 v0, v2, v0
	v_fma_f32 v0, v2, v0, v2
	v_mul_f32_e32 v0, 0x3f4c422a, v0
	v_add_f32_e32 v0, v0, v0
	v_mul_f32_e32 v0, 0xbfb8aa3b, v0
	v_exp_f32_e32 v0, v0
	s_nop 0
	v_add_f32_e32 v0, 1.0, v0
	v_rcp_f32_e32 v0, v0
	s_nop 0
	v_mul_f32_e32 v1, 0x3d372713, v3
	v_mul_f32_e32 v1, v3, v1
	v_fma_f32 v1, v3, v1, v3
	v_mul_f32_e32 v1, 0x3f4c422a, v1
	v_add_f32_e32 v1, v1, v1
	v_mul_f32_e32 v1, 0xbfb8aa3b, v1
	v_exp_f32_e32 v1, v1
	v_mul_f32_e32 v0, v2, v0
	v_add_f32_e32 v1, 1.0, v1
	v_rcp_f32_e32 v1, v1
	s_nop 0
	v_mul_f32_e32 v1, v3, v1
	v_cvt_pk_bf16_f32 v7, v0, v1
	v_lshl_add_u64 v[0:1], v[8:9], 0, v[112:113]
	v_lshl_add_u64 v[0:1], v[0:1], 0, s[22:23]
	v_lshl_add_u64 v[0:1], v[0:1], 0, v[224:225]
	s_mov_b64 s[22:23], -1
	s_andn2_b64 vcc, exec, s[4:5]
	global_store_dwordx4 v[0:1], v[4:7], off
	s_cbranch_vccnz .LBB0_530
	s_andn2_b64 vcc, exec, s[6:7]
	s_cbranch_vccnz .LBB0_529
	s_barrier
	s_branch .LBB0_529

; __device__ __forceinline__ unsigned cvt_pk_bf16(float lo, float hi) { unsigned r; asm volatile("v_cvt_pk_bf16_f32 %0, %1, %2" : "=v"(r) : "v"(lo), "v"(hi)); return r; }
; __device__ __forceinline__ float bflo(unsigned w) { return __uint_as_float(w << 16); }
; __device__ __forceinline__ float bfhi(unsigned w) { return __uint_as_float(w & 0xffff0000u); }
; __device__ __forceinline__ float silu_f(float z) { return z / (1.0f + __expf(-z)); }
; __device__ __forceinline__ float sigmoid_f(float z) { return 1.0f / (1.0f + __expf(-z)); }
;     __device__ __forceinline__ void operator()(const AccT& acc, const Unit& u, int wr, int wc, int fr, int fq) const {
;         bf16_t* OCAT = (bf16_t*)(ws + WS_H); const bf16_t* PROJ = (const bf16_t*)(ws + WS_PROJ);
;         const int lc = u.pn * 128 + wc * 32 + 8 * fq;
;         const f32x4 bl0 = *(const f32x4*)(bglu + lc), bl1 = *(const f32x4*)(bglu + lc + 4), bg0 = *(const f32x4*)(bglu + 1024 + lc), bg1 = *(const f32x4*)(bglu + 1024 + lc + 4);
; #pragma unroll
;         for (int ai = 0; ai < 2; ++ai)
; #pragma unroll
;             for (int m = 0; m < 4; ++m) {
;                 const int row = u.pm * 256 + ai * 128 + wr * 64 + m * 16 + fr;
;                 const u32x4 z = *(const u32x4*)(PROJ + (size_t)row * PP + C_ZS + lc);
;                 const f32x4 l0 = acc[ai][0][m][0] + bl0, l1 = acc[ai][0][m][1] + bl1, g0 = acc[ai][1][m][0] + bg0, g1 = acc[ai][1][m][1] + bg1;
;                 float o[8];
;                 o[0] = l0[0] * sigmoid_f(g0[0]) * silu_f(bflo(z.x)); o[1] = l0[1] * sigmoid_f(g0[1]) * silu_f(bfhi(z.x));
;                 o[2] = l0[2] * sigmoid_f(g0[2]) * silu_f(bflo(z.y)); o[3] = l0[3] * sigmoid_f(g0[3]) * silu_f(bfhi(z.y));
;                 o[4] = l1[0] * sigmoid_f(g1[0]) * silu_f(bflo(z.z)); o[5] = l1[1] * sigmoid_f(g1[1]) * silu_f(bfhi(z.z));
;                 o[6] = l1[2] * sigmoid_f(g1[2]) * silu_f(bflo(z.w)); o[7] = l1[3] * sigmoid_f(g1[3]) * silu_f(bfhi(z.w));
;                 u32x4 w; w.x = cvt_pk_bf16(o[0], o[1]); w.y = cvt_pk_bf16(o[2], o[3]); w.z = cvt_pk_bf16(o[4], o[5]); w.w = cvt_pk_bf16(o[6], o[7]);
;                 *(u32x4*)(OCAT + (size_t)row * 2048 + 1024 + lc) = w;
;                 if (m == 3) asm volatile("" ::: "memory");
;             }
;     }
.LBB0_609:
	v_lshl_or_b32 v128, s38, 7, v166
	v_ashrrev_i32_e32 v129, 31, v128
	v_lshl_add_u32 v168, s37, 8, v164
	v_mov_b64_e32 v[160:161], s[6:7]
	v_lshlrev_b64 v[16:17], 2, v[128:129]
	v_mad_i64_i32 v[162:163], s[30:31], v168, s52, v[160:161]
	v_lshlrev_b64 v[158:159], 1, v[128:129]
	v_lshl_add_u64 v[18:19], s[16:17], 0, v[16:17]
	v_lshl_add_u64 v[20:21], s[18:19], 0, v[16:17]
	v_lshl_add_u64 v[128:129], v[162:163], 0, v[158:159]
	global_load_dwordx4 v[24:27], v[18:19], off offset:16
	global_load_dwordx4 v[28:31], v[18:19], off
	s_nop 0
	global_load_dwordx4 v[16:19], v[20:21], off offset:16
	s_nop 0
	global_load_dwordx4 v[20:23], v[20:21], off
	v_add_co_u32_e32 v128, vcc, s63, v128
	s_waitcnt vmcnt(0)
	v_pk_add_f32 v[140:141], v[140:141], v[24:25]
	v_addc_co_u32_e32 v129, vcc, 0, v129, vcc
	global_load_dwordx4 v[128:131], v[128:129], off
	v_pk_add_f32 v[136:137], v[136:137], v[20:21]
	v_pk_add_f32 v[144:145], v[144:145], v[28:29]
	v_mul_f32_e32 v136, 0xbfb8aa3b, v136
	v_exp_f32_e32 v170, v136
	v_pk_add_f32 v[138:139], v[138:139], v[22:23]
	v_pk_add_f32 v[146:147], v[146:147], v[30:31]
	v_pk_add_f32 v[132:133], v[132:133], v[16:17]
	v_pk_add_f32 v[134:135], v[134:135], v[18:19]
	v_mul_f32_e32 v132, 0xbfb8aa3b, v132
	v_pk_add_f32 v[142:143], v[142:143], v[26:27]
	v_pk_add_f32 v[116:117], v[116:117], v[20:21]
	v_pk_add_f32 v[124:125], v[124:125], v[28:29]
	v_mul_f32_e32 v116, 0xbfb8aa3b, v116
	v_mul_f32_e32 v117, 0xbfb8aa3b, v117
	v_pk_add_f32 v[118:119], v[118:119], v[22:23]
	v_pk_add_f32 v[126:127], v[126:127], v[30:31]
	v_mul_f32_e32 v118, 0xbfb8aa3b, v118
	v_mul_f32_e32 v119, 0xbfb8aa3b, v119
	v_pk_add_f32 v[112:113], v[112:113], v[16:17]
	v_pk_add_f32 v[120:121], v[120:121], v[24:25]
	v_mul_f32_e32 v112, 0xbfb8aa3b, v112
	v_pk_add_f32 v[114:115], v[114:115], v[18:19]
	v_pk_add_f32 v[122:123], v[122:123], v[26:27]
	v_pk_add_f32 v[100:101], v[100:101], v[20:21]
	v_pk_add_f32 v[108:109], v[108:109], v[28:29]
	v_mul_f32_e32 v100, 0xbfb8aa3b, v100
	v_mul_f32_e32 v101, 0xbfb8aa3b, v101
	v_pk_add_f32 v[102:103], v[102:103], v[22:23]
	v_pk_add_f32 v[110:111], v[110:111], v[30:31]
	v_mul_f32_e32 v102, 0xbfb8aa3b, v102
	v_mul_f32_e32 v103, 0xbfb8aa3b, v103
	v_pk_add_f32 v[96:97], v[96:97], v[16:17]
	v_pk_add_f32 v[104:105], v[104:105], v[24:25]
	v_mul_f32_e32 v96, 0xbfb8aa3b, v96
	v_pk_add_f32 v[98:99], v[98:99], v[18:19]
	v_pk_add_f32 v[106:107], v[106:107], v[26:27]
	v_pk_add_f32 v[84:85], v[84:85], v[20:21]
	v_pk_add_f32 v[92:93], v[92:93], v[28:29]
	v_mul_f32_e32 v84, 0xbfb8aa3b, v84
	v_mul_f32_e32 v85, 0xbfb8aa3b, v85
	v_pk_add_f32 v[86:87], v[86:87], v[22:23]
	v_pk_add_f32 v[94:95], v[94:95], v[30:31]
	v_mul_f32_e32 v86, 0xbfb8aa3b, v86
	v_mul_f32_e32 v87, 0xbfb8aa3b, v87
	v_pk_add_f32 v[80:81], v[80:81], v[16:17]
	v_pk_add_f32 v[88:89], v[88:89], v[24:25]
	v_mul_f32_e32 v80, 0xbfb8aa3b, v80
	v_pk_add_f32 v[82:83], v[82:83], v[18:19]
	v_pk_add_f32 v[90:91], v[90:91], v[26:27]
	v_pk_add_f32 v[68:69], v[68:69], v[20:21]
	v_pk_add_f32 v[76:77], v[76:77], v[28:29]
	v_mul_f32_e32 v68, 0xbfb8aa3b, v68
	v_mul_f32_e32 v69, 0xbfb8aa3b, v69
	v_pk_add_f32 v[70:71], v[70:71], v[22:23]
	v_pk_add_f32 v[78:79], v[78:79], v[30:31]
	v_mul_f32_e32 v70, 0xbfb8aa3b, v70
	v_mul_f32_e32 v71, 0xbfb8aa3b, v71
	v_pk_add_f32 v[64:65], v[64:65], v[16:17]
	v_pk_add_f32 v[72:73], v[72:73], v[24:25]
	v_mul_f32_e32 v64, 0xbfb8aa3b, v64
	v_pk_add_f32 v[66:67], v[66:67], v[18:19]
	v_pk_add_f32 v[74:75], v[74:75], v[26:27]
	v_pk_add_f32 v[52:53], v[52:53], v[20:21]
	v_pk_add_f32 v[60:61], v[60:61], v[28:29]
	v_mul_f32_e32 v52, 0xbfb8aa3b, v52
	v_mul_f32_e32 v53, 0xbfb8aa3b, v53
	v_pk_add_f32 v[54:55], v[54:55], v[22:23]
	v_pk_add_f32 v[62:63], v[62:63], v[30:31]
	v_mul_f32_e32 v54, 0xbfb8aa3b, v54
	v_mul_f32_e32 v55, 0xbfb8aa3b, v55
	v_pk_add_f32 v[48:49], v[48:49], v[16:17]
	v_pk_add_f32 v[56:57], v[56:57], v[24:25]
	v_mul_f32_e32 v48, 0xbfb8aa3b, v48
	v_pk_add_f32 v[50:51], v[50:51], v[18:19]
	v_pk_add_f32 v[58:59], v[58:59], v[26:27]
	v_pk_add_f32 v[36:37], v[36:37], v[20:21]
	v_pk_add_f32 v[44:45], v[44:45], v[28:29]
	v_mul_f32_e32 v36, 0xbfb8aa3b, v36
	v_mul_f32_e32 v37, 0xbfb8aa3b, v37
	s_waitcnt vmcnt(0)
	v_lshlrev_b32_e32 v136, 16, v128
	v_mul_f32_e32 v169, 0xbfb8aa3b, v136
	v_exp_f32_e32 v171, v169
	v_and_b32_e32 v128, 0xffff0000, v128
	v_pk_add_f32 v[38:39], v[38:39], v[22:23]
	v_pk_add_f32 v[46:47], v[46:47], v[30:31]
	v_pk_add_f32 v[170:171], v[170:171], 1.0 op_sel_hi:[1,0]
	v_mul_f32_e32 v38, 0xbfb8aa3b, v38
	v_mul_f32_e32 v39, 0xbfb8aa3b, v39
	v_pk_add_f32 v[32:33], v[32:33], v[16:17]
	v_pk_add_f32 v[40:41], v[40:41], v[24:25]
	v_rcp_f32_e32 v169, v171
	s_nop 0
	v_mul_f32_e32 v136, v136, v169
	v_mul_f32_e32 v32, 0xbfb8aa3b, v32
	v_pk_add_f32 v[34:35], v[34:35], v[18:19]
	v_pk_add_f32 v[42:43], v[42:43], v[26:27]
	v_rcp_f32_e32 v169, v170
	s_nop 0
	v_mul_f32_e32 v144, v144, v169
	v_mul_f32_e32 v144, v144, v136
	v_mul_f32_e32 v136, 0xbfb8aa3b, v137
	v_mul_f32_e32 v137, 0xbfb8aa3b, v128
	v_exp_f32_e32 v136, v136
	v_exp_f32_e32 v137, v137
	v_pk_add_f32 v[4:5], v[4:5], v[20:21]
	v_pk_add_f32 v[0:1], v[0:1], v[16:17]
	v_mul_f32_e32 v4, 0xbfb8aa3b, v4
	v_pk_add_f32 v[136:137], v[136:137], 1.0 op_sel_hi:[1,0]
	v_exp_f32_e32 v16, v4
	v_pk_add_f32 v[2:3], v[2:3], v[18:19]
	v_pk_add_f32 v[6:7], v[6:7], v[22:23]
	v_pk_add_f32 v[12:13], v[12:13], v[28:29]
	v_rcp_f32_e32 v169, v137
	s_nop 0
	v_mul_f32_e32 v128, v128, v169
	v_mul_f32_e32 v5, 0xbfb8aa3b, v5
	v_mul_f32_e32 v6, 0xbfb8aa3b, v6
	v_pk_add_f32 v[14:15], v[14:15], v[30:31]
	v_rcp_f32_e32 v136, v136
	s_nop 0
	v_mul_f32_e32 v136, v145, v136
	v_mul_f32_e32 v128, v136, v128
	v_mul_f32_e32 v136, 0xbfb8aa3b, v138
; __device__ __forceinline__ unsigned cvt_pk_bf16(float lo, float hi) { unsigned r; asm volatile("v_cvt_pk_bf16_f32 %0, %1, %2" : "=v"(r) : "v"(lo), "v"(hi)); return r; }
; __device__ __forceinline__ float bflo(unsigned w) { return __uint_as_float(w << 16); }
; __device__ __forceinline__ float bfhi(unsigned w) { return __uint_as_float(w & 0xffff0000u); }
; __device__ __forceinline__ float silu_f(float z) { return z / (1.0f + __expf(-z)); }
; __device__ __forceinline__ float sigmoid_f(float z) { return 1.0f / (1.0f + __expf(-z)); }
;     __device__ __forceinline__ void operator()(const AccT& acc, const Unit& u, int wr, int wc, int fr, int fq) const {
;         bf16_t* OCAT = (bf16_t*)(ws + WS_H); const bf16_t* PROJ = (const bf16_t*)(ws + WS_PROJ);
;         const int lc = u.pn * 128 + wc * 32 + 8 * fq;
;         const f32x4 bl0 = *(const f32x4*)(bglu + lc), bl1 = *(const f32x4*)(bglu + lc + 4), bg0 = *(const f32x4*)(bglu + 1024 + lc), bg1 = *(const f32x4*)(bglu + 1024 + lc + 4);
; #pragma unroll
;         for (int ai = 0; ai < 2; ++ai)
; #pragma unroll
;             for (int m = 0; m < 4; ++m) {
;                 const int row = u.pm * 256 + ai * 128 + wr * 64 + m * 16 + fr;
;                 const u32x4 z = *(const u32x4*)(PROJ + (size_t)row * PP + C_ZS + lc);
;                 const f32x4 l0 = acc[ai][0][m][0] + bl0, l1 = acc[ai][0][m][1] + bl1, g0 = acc[ai][1][m][0] + bg0, g1 = acc[ai][1][m][1] + bg1;
;                 float o[8];
;                 o[0] = l0[0] * sigmoid_f(g0[0]) * silu_f(bflo(z.x)); o[1] = l0[1] * sigmoid_f(g0[1]) * silu_f(bfhi(z.x));
;                 o[2] = l0[2] * sigmoid_f(g0[2]) * silu_f(bflo(z.y)); o[3] = l0[3] * sigmoid_f(g0[3]) * silu_f(bfhi(z.y));
;                 o[4] = l1[0] * sigmoid_f(g1[0]) * silu_f(bflo(z.z)); o[5] = l1[1] * sigmoid_f(g1[1]) * silu_f(bfhi(z.z));
;                 o[6] = l1[2] * sigmoid_f(g1[2]) * silu_f(bflo(z.w)); o[7] = l1[3] * sigmoid_f(g1[3]) * silu_f(bfhi(z.w));
;                 u32x4 w; w.x = cvt_pk_bf16(o[0], o[1]); w.y = cvt_pk_bf16(o[2], o[3]); w.z = cvt_pk_bf16(o[4], o[5]); w.w = cvt_pk_bf16(o[6], o[7]);
;                 *(u32x4*)(OCAT + (size_t)row * 2048 + 1024 + lc) = w;
;                 if (m == 3) asm volatile("" ::: "memory");
;             }
;     }
	v_lshlrev_b32_e32 v138, 16, v129
	v_mul_f32_e32 v137, 0xbfb8aa3b, v138
	v_exp_f32_e32 v136, v136
	v_exp_f32_e32 v137, v137
	v_and_b32_e32 v129, 0xffff0000, v129
	v_cvt_pk_bf16_f32 v128, v144, v128
	v_mul_f32_e32 v7, 0xbfb8aa3b, v7
	v_pk_add_f32 v[136:137], v[136:137], 1.0 op_sel_hi:[1,0]
	v_mul_f32_e32 v0, 0xbfb8aa3b, v0
	v_pk_add_f32 v[8:9], v[8:9], v[24:25]
	v_pk_add_f32 v[10:11], v[10:11], v[26:27]
	v_rcp_f32_e32 v145, v137
	s_nop 0
	v_mul_f32_e32 v137, v138, v145
	v_rcp_f32_e32 v136, v136
	s_nop 0
	v_mul_f32_e32 v136, v146, v136
	v_mul_f32_e32 v136, v136, v137
	v_mul_f32_e32 v137, 0xbfb8aa3b, v139
	v_exp_f32_e32 v138, v137
	v_mul_f32_e32 v137, 0xbfb8aa3b, v129
	v_exp_f32_e32 v139, v137
	s_nop 0
	v_pk_add_f32 v[138:139], v[138:139], 1.0 op_sel_hi:[1,0]
	s_nop 0
	v_rcp_f32_e32 v137, v139
	s_nop 0
	v_mul_f32_e32 v129, v129, v137
	v_rcp_f32_e32 v137, v138
	s_nop 0
	v_mul_f32_e32 v137, v147, v137
	v_exp_f32_e32 v138, v132
	v_lshlrev_b32_e32 v132, 16, v130
	v_mul_f32_e32 v129, v137, v129
	v_mul_f32_e32 v137, 0xbfb8aa3b, v132
	v_exp_f32_e32 v139, v137
	v_and_b32_e32 v130, 0xffff0000, v130
	v_cvt_pk_bf16_f32 v129, v136, v129
	v_exp_f32_e32 v136, v116
	v_pk_add_f32 v[138:139], v[138:139], 1.0 op_sel_hi:[1,0]
	s_nop 0
	v_rcp_f32_e32 v137, v139
	s_nop 0
	v_mul_f32_e32 v132, v132, v137
	v_rcp_f32_e32 v137, v138
	s_nop 0
	v_mul_f32_e32 v137, v140, v137
	v_mul_f32_e32 v137, v137, v132
	v_mul_f32_e32 v132, 0xbfb8aa3b, v133
	v_mul_f32_e32 v133, 0xbfb8aa3b, v130
	v_exp_f32_e32 v132, v132
	v_exp_f32_e32 v133, v133
	s_nop 0
	v_pk_add_f32 v[132:133], v[132:133], 1.0 op_sel_hi:[1,0]
	s_nop 0
	v_rcp_f32_e32 v138, v133
	s_nop 0
	v_mul_f32_e32 v130, v130, v138
	v_rcp_f32_e32 v132, v132
	s_nop 0
	v_mul_f32_e32 v132, v141, v132
	v_mul_f32_e32 v138, v132, v130
	v_mul_f32_e32 v130, 0xbfb8aa3b, v134
	v_exp_f32_e32 v132, v130
	v_lshlrev_b32_e32 v130, 16, v131
	v_mul_f32_e32 v133, 0xbfb8aa3b, v130
	v_exp_f32_e32 v133, v133
	s_nop 0
	v_pk_add_f32 v[132:133], v[132:133], 1.0 op_sel_hi:[1,0]
	s_nop 0
	v_rcp_f32_e32 v134, v133
	s_nop 0
	v_mul_f32_e32 v130, v130, v134
	v_rcp_f32_e32 v132, v132
	s_nop 0
	v_mul_f32_e32 v132, v142, v132
	v_and_b32_e32 v133, 0xffff0000, v131
	v_mul_f32_e32 v132, v132, v130
	v_mul_f32_e32 v130, 0xbfb8aa3b, v135
	v_mul_f32_e32 v131, 0xbfb8aa3b, v133
	v_exp_f32_e32 v130, v130
	v_exp_f32_e32 v131, v131
	s_nop 0
	v_pk_add_f32 v[130:131], v[130:131], 1.0 op_sel_hi:[1,0]
	s_nop 0
	v_rcp_f32_e32 v134, v131
	s_nop 0
	v_mul_f32_e32 v131, v133, v134
	v_rcp_f32_e32 v130, v130
	s_nop 0
	v_mul_f32_e32 v130, v143, v130
	v_mul_f32_e32 v131, v130, v131
	v_cvt_pk_bf16_f32 v130, v137, v138
	v_cvt_pk_bf16_f32 v131, v132, v131
	v_mad_i64_i32 v[132:133], s[30:31], v168, s66, v[162:163]
	v_lshl_add_u64 v[132:133], v[132:133], 0, v[158:159]
	v_add_co_u32_e32 v132, vcc, s67, v132
	v_or_b32_e32 v134, 16, v168
	s_nop 0
	v_addc_co_u32_e32 v133, vcc, 0, v133, vcc
	global_store_dwordx4 v[132:133], v[128:131], off offset:2048
	v_mad_i64_i32 v[132:133], s[30:31], v134, s52, v[160:161]
	s_nop 0
	v_lshl_add_u64 v[128:129], v[132:133], 0, v[158:159]
	v_add_co_u32_e32 v128, vcc, s63, v128
	s_nop 1
	v_addc_co_u32_e32 v129, vcc, 0, v129, vcc
	global_load_dwordx4 v[128:131], v[128:129], off
	s_waitcnt vmcnt(0)
	v_lshlrev_b32_e32 v116, 16, v128
	v_mul_f32_e32 v135, 0xbfb8aa3b, v116
	v_exp_f32_e32 v137, v135
	s_nop 0
	v_pk_add_f32 v[136:137], v[136:137], 1.0 op_sel_hi:[1,0]
	s_nop 0
	v_rcp_f32_e32 v135, v137
	s_nop 0
	v_mul_f32_e32 v116, v116, v135
	v_rcp_f32_e32 v135, v136
	s_nop 0
	v_mul_f32_e32 v124, v124, v135
	v_exp_f32_e32 v136, v117
	v_and_b32_e32 v117, 0xffff0000, v128
	v_mul_f32_e32 v116, v124, v116
	v_mul_f32_e32 v124, 0xbfb8aa3b, v117
	v_exp_f32_e32 v137, v124
	s_nop 0
	v_pk_add_f32 v[136:137], v[136:137], 1.0 op_sel_hi:[1,0]
	s_nop 0
	v_rcp_f32_e32 v124, v137
	s_nop 0
	v_mul_f32_e32 v117, v117, v124
	v_rcp_f32_e32 v124, v136
	s_nop 0
	v_mul_f32_e32 v124, v125, v124
	v_mul_f32_e32 v117, v124, v117
	v_exp_f32_e32 v124, v118
	v_lshlrev_b32_e32 v118, 16, v129
	v_mul_f32_e32 v125, 0xbfb8aa3b, v118
	v_exp_f32_e32 v125, v125
	s_nop 0
	v_pk_add_f32 v[124:125], v[124:125], 1.0 op_sel_hi:[1,0]
	s_nop 0
	v_rcp_f32_e32 v128, v125
	s_nop 0
	v_mul_f32_e32 v118, v118, v128
	v_rcp_f32_e32 v124, v124
	s_nop 0
	v_mul_f32_e32 v124, v126, v124
	v_mul_f32_e32 v118, v124, v118
	v_exp_f32_e32 v124, v119
	v_and_b32_e32 v119, 0xffff0000, v129
	v_mul_f32_e32 v125, 0xbfb8aa3b, v119
	v_exp_f32_e32 v125, v125
	s_nop 0
	v_pk_add_f32 v[124:125], v[124:125], 1.0 op_sel_hi:[1,0]
	s_nop 0
	v_rcp_f32_e32 v126, v125
	s_nop 0
	v_mul_f32_e32 v119, v119, v126
	v_rcp_f32_e32 v124, v124
	s_nop 0
	v_mul_f32_e32 v124, v127, v124
	v_mul_f32_e32 v119, v124, v119
	v_exp_f32_e32 v124, v112
	v_lshlrev_b32_e32 v112, 16, v130
	v_mul_f32_e32 v125, 0xbfb8aa3b, v112
	v_exp_f32_e32 v125, v125
	s_nop 0
	v_pk_add_f32 v[124:125], v[124:125], 1.0 op_sel_hi:[1,0]
	s_nop 0
	v_rcp_f32_e32 v126, v125
	s_nop 0
	v_mul_f32_e32 v112, v112, v126
	v_rcp_f32_e32 v124, v124
	s_nop 0
	v_mul_f32_e32 v120, v120, v124
	v_and_b32_e32 v124, 0xffff0000, v130
	v_mul_f32_e32 v120, v120, v112
	v_mul_f32_e32 v112, 0xbfb8aa3b, v113
	v_mul_f32_e32 v113, 0xbfb8aa3b, v124
	v_exp_f32_e32 v112, v112
	v_exp_f32_e32 v113, v113
	s_nop 0
	v_pk_add_f32 v[112:113], v[112:113], 1.0 op_sel_hi:[1,0]
	s_nop 0
	v_rcp_f32_e32 v125, v113
	s_nop 0
	v_mul_f32_e32 v113, v124, v125
	v_rcp_f32_e32 v112, v112
	s_nop 0
	v_mul_f32_e32 v112, v121, v112
	v_mul_f32_e32 v121, v112, v113
	v_mul_f32_e32 v112, 0xbfb8aa3b, v114
	v_lshlrev_b32_e32 v114, 16, v131
	v_mul_f32_e32 v113, 0xbfb8aa3b, v114
	v_exp_f32_e32 v112, v112
	v_exp_f32_e32 v113, v113
	s_nop 0
	v_pk_add_f32 v[112:113], v[112:113], 1.0 op_sel_hi:[1,0]
	s_nop 0
	v_rcp_f32_e32 v124, v113
	s_nop 0
	v_mul_f32_e32 v113, v114, v124
	v_rcp_f32_e32 v112, v112
	s_nop 0
	v_mul_f32_e32 v112, v122, v112
	v_and_b32_e32 v114, 0xffff0000, v131
	v_mul_f32_e32 v122, v112, v113
	v_mul_f32_e32 v112, 0xbfb8aa3b, v115
	v_mul_f32_e32 v113, 0xbfb8aa3b, v114
	v_exp_f32_e32 v112, v112
	v_exp_f32_e32 v113, v113
	s_nop 0
	v_pk_add_f32 v[112:113], v[112:113], 1.0 op_sel_hi:[1,0]
	s_nop 0
	v_rcp_f32_e32 v115, v113
	s_nop 0
	v_mul_f32_e32 v113, v114, v115
	v_rcp_f32_e32 v112, v112
	s_nop 0
	v_mul_f32_e32 v112, v123, v112
	v_mul_f32_e32 v115, v112, v113
	v_cvt_pk_bf16_f32 v112, v116, v117
	v_mad_i64_i32 v[116:117], s[30:31], v134, s66, v[132:133]
	v_lshl_add_u64 v[116:117], v[116:117], 0, v[158:159]
	v_add_co_u32_e32 v116, vcc, s67, v116
	v_cvt_pk_bf16_f32 v113, v118, v119
	v_or_b32_e32 v118, 32, v168
	s_nop 0
	v_addc_co_u32_e32 v117, vcc, 0, v117, vcc
	v_cvt_pk_bf16_f32 v114, v120, v121
	v_cvt_pk_bf16_f32 v115, v122, v115
	global_store_dwordx4 v[116:117], v[112:115], off offset:2048
	v_mad_i64_i32 v[116:117], s[30:31], v118, s52, v[160:161]
	s_nop 0
	v_lshl_add_u64 v[112:113], v[116:117], 0, v[158:159]
	v_add_co_u32_e32 v112, vcc, s63, v112
	v_exp_f32_e32 v120, v100
	s_nop 0
	v_addc_co_u32_e32 v113, vcc, 0, v113, vcc
	global_load_dwordx4 v[112:115], v[112:113], off
	s_waitcnt vmcnt(0)
; __device__ __forceinline__ unsigned cvt_pk_bf16(float lo, float hi) { unsigned r; asm volatile("v_cvt_pk_bf16_f32 %0, %1, %2" : "=v"(r) : "v"(lo), "v"(hi)); return r; }
; __device__ __forceinline__ float bflo(unsigned w) { return __uint_as_float(w << 16); }
; __device__ __forceinline__ float bfhi(unsigned w) { return __uint_as_float(w & 0xffff0000u); }
; __device__ __forceinline__ float silu_f(float z) { return z / (1.0f + __expf(-z)); }
; __device__ __forceinline__ float sigmoid_f(float z) { return 1.0f / (1.0f + __expf(-z)); }
;     __device__ __forceinline__ void operator()(const AccT& acc, const Unit& u, int wr, int wc, int fr, int fq) const {
;         bf16_t* OCAT = (bf16_t*)(ws + WS_H); const bf16_t* PROJ = (const bf16_t*)(ws + WS_PROJ);
;         const int lc = u.pn * 128 + wc * 32 + 8 * fq;
;         const f32x4 bl0 = *(const f32x4*)(bglu + lc), bl1 = *(const f32x4*)(bglu + lc + 4), bg0 = *(const f32x4*)(bglu + 1024 + lc), bg1 = *(const f32x4*)(bglu + 1024 + lc + 4);
; #pragma unroll
;         for (int ai = 0; ai < 2; ++ai)
; #pragma unroll
;             for (int m = 0; m < 4; ++m) {
;                 const int row = u.pm * 256 + ai * 128 + wr * 64 + m * 16 + fr;
;                 const u32x4 z = *(const u32x4*)(PROJ + (size_t)row * PP + C_ZS + lc);
;                 const f32x4 l0 = acc[ai][0][m][0] + bl0, l1 = acc[ai][0][m][1] + bl1, g0 = acc[ai][1][m][0] + bg0, g1 = acc[ai][1][m][1] + bg1;
;                 float o[8];
;                 o[0] = l0[0] * sigmoid_f(g0[0]) * silu_f(bflo(z.x)); o[1] = l0[1] * sigmoid_f(g0[1]) * silu_f(bfhi(z.x));
;                 o[2] = l0[2] * sigmoid_f(g0[2]) * silu_f(bflo(z.y)); o[3] = l0[3] * sigmoid_f(g0[3]) * silu_f(bfhi(z.y));
;                 o[4] = l1[0] * sigmoid_f(g1[0]) * silu_f(bflo(z.z)); o[5] = l1[1] * sigmoid_f(g1[1]) * silu_f(bfhi(z.z));
;                 o[6] = l1[2] * sigmoid_f(g1[2]) * silu_f(bflo(z.w)); o[7] = l1[3] * sigmoid_f(g1[3]) * silu_f(bfhi(z.w));
;                 u32x4 w; w.x = cvt_pk_bf16(o[0], o[1]); w.y = cvt_pk_bf16(o[2], o[3]); w.z = cvt_pk_bf16(o[4], o[5]); w.w = cvt_pk_bf16(o[6], o[7]);
;                 *(u32x4*)(OCAT + (size_t)row * 2048 + 1024 + lc) = w;
;                 if (m == 3) asm volatile("" ::: "memory");
;             }
;     }
	v_lshlrev_b32_e32 v100, 16, v112
	v_mul_f32_e32 v119, 0xbfb8aa3b, v100
	v_exp_f32_e32 v121, v119
	s_nop 0
	v_pk_add_f32 v[120:121], v[120:121], 1.0 op_sel_hi:[1,0]
	s_nop 0
	v_rcp_f32_e32 v119, v121
	s_nop 0
	v_mul_f32_e32 v100, v100, v119
	v_rcp_f32_e32 v119, v120
	s_nop 0
	v_mul_f32_e32 v108, v108, v119
	v_exp_f32_e32 v120, v101
	v_and_b32_e32 v101, 0xffff0000, v112
	v_mul_f32_e32 v100, v108, v100
	v_mul_f32_e32 v108, 0xbfb8aa3b, v101
	v_exp_f32_e32 v121, v108
	s_nop 0
	v_pk_add_f32 v[120:121], v[120:121], 1.0 op_sel_hi:[1,0]
	s_nop 0
	v_rcp_f32_e32 v108, v121
	s_nop 0
	v_mul_f32_e32 v101, v101, v108
	v_rcp_f32_e32 v108, v120
	s_nop 0
	v_mul_f32_e32 v108, v109, v108
	v_mul_f32_e32 v101, v108, v101
	v_exp_f32_e32 v108, v102
	v_lshlrev_b32_e32 v102, 16, v113
	v_mul_f32_e32 v109, 0xbfb8aa3b, v102
	v_exp_f32_e32 v109, v109
	s_nop 0
	v_pk_add_f32 v[108:109], v[108:109], 1.0 op_sel_hi:[1,0]
	s_nop 0
	v_rcp_f32_e32 v112, v109
	s_nop 0
	v_mul_f32_e32 v102, v102, v112
	v_rcp_f32_e32 v108, v108
	s_nop 0
	v_mul_f32_e32 v108, v110, v108
	v_mul_f32_e32 v102, v108, v102
	v_exp_f32_e32 v108, v103
	v_and_b32_e32 v103, 0xffff0000, v113
	v_mul_f32_e32 v109, 0xbfb8aa3b, v103
	v_exp_f32_e32 v109, v109
	s_nop 0
	v_pk_add_f32 v[108:109], v[108:109], 1.0 op_sel_hi:[1,0]
	s_nop 0
	v_rcp_f32_e32 v110, v109
	s_nop 0
	v_mul_f32_e32 v103, v103, v110
	v_rcp_f32_e32 v108, v108
	s_nop 0
	v_mul_f32_e32 v108, v111, v108
	v_mul_f32_e32 v103, v108, v103
	v_exp_f32_e32 v108, v96
	v_lshlrev_b32_e32 v96, 16, v114
	v_mul_f32_e32 v109, 0xbfb8aa3b, v96
	v_exp_f32_e32 v109, v109
	s_nop 0
	v_pk_add_f32 v[108:109], v[108:109], 1.0 op_sel_hi:[1,0]
	s_nop 0
	v_rcp_f32_e32 v110, v109
	s_nop 0
	v_mul_f32_e32 v96, v96, v110
	v_rcp_f32_e32 v108, v108
	s_nop 0
	v_mul_f32_e32 v104, v104, v108
	v_and_b32_e32 v108, 0xffff0000, v114
	v_mul_f32_e32 v104, v104, v96
	v_mul_f32_e32 v96, 0xbfb8aa3b, v97
	v_mul_f32_e32 v97, 0xbfb8aa3b, v108
	v_exp_f32_e32 v96, v96
	v_exp_f32_e32 v97, v97
	s_nop 0
	v_pk_add_f32 v[96:97], v[96:97], 1.0 op_sel_hi:[1,0]
	s_nop 0
	v_rcp_f32_e32 v109, v97
	s_nop 0
	v_mul_f32_e32 v97, v108, v109
	v_rcp_f32_e32 v96, v96
	s_nop 0
	v_mul_f32_e32 v96, v105, v96
	v_mul_f32_e32 v105, v96, v97
	v_mul_f32_e32 v96, 0xbfb8aa3b, v98
	v_lshlrev_b32_e32 v98, 16, v115
	v_mul_f32_e32 v97, 0xbfb8aa3b, v98
	v_exp_f32_e32 v96, v96
	v_exp_f32_e32 v97, v97
	s_nop 0
	v_pk_add_f32 v[96:97], v[96:97], 1.0 op_sel_hi:[1,0]
	s_nop 0
	v_rcp_f32_e32 v108, v97
	s_nop 0
	v_mul_f32_e32 v97, v98, v108
	v_rcp_f32_e32 v96, v96
	s_nop 0
	v_mul_f32_e32 v96, v106, v96
	v_and_b32_e32 v98, 0xffff0000, v115
	v_mul_f32_e32 v106, v96, v97
	v_mul_f32_e32 v96, 0xbfb8aa3b, v99
	v_mul_f32_e32 v97, 0xbfb8aa3b, v98
	v_exp_f32_e32 v96, v96
	v_exp_f32_e32 v97, v97
	s_nop 0
	v_pk_add_f32 v[96:97], v[96:97], 1.0 op_sel_hi:[1,0]
	s_nop 0
	v_rcp_f32_e32 v99, v97
	s_nop 0
	v_mul_f32_e32 v97, v98, v99
	v_rcp_f32_e32 v96, v96
	s_nop 0
	v_mul_f32_e32 v96, v107, v96
	v_mul_f32_e32 v99, v96, v97
	v_cvt_pk_bf16_f32 v96, v100, v101
	v_mad_i64_i32 v[100:101], s[30:31], v118, s66, v[116:117]
	v_lshl_add_u64 v[100:101], v[100:101], 0, v[158:159]
	v_add_co_u32_e32 v100, vcc, s67, v100
	v_cvt_pk_bf16_f32 v97, v102, v103
	v_or_b32_e32 v102, 48, v168
	s_nop 0
	v_addc_co_u32_e32 v101, vcc, 0, v101, vcc
	v_cvt_pk_bf16_f32 v98, v104, v105
	v_cvt_pk_bf16_f32 v99, v106, v99
	global_store_dwordx4 v[100:101], v[96:99], off offset:2048
	v_mad_i64_i32 v[100:101], s[30:31], v102, s52, v[160:161]
	s_nop 0
	v_lshl_add_u64 v[96:97], v[100:101], 0, v[158:159]
	v_add_co_u32_e32 v96, vcc, s63, v96
	v_exp_f32_e32 v104, v84
	s_nop 0
	v_addc_co_u32_e32 v97, vcc, 0, v97, vcc
	global_load_dwordx4 v[96:99], v[96:97], off
	s_waitcnt vmcnt(0)
	v_lshlrev_b32_e32 v84, 16, v96
	v_mul_f32_e32 v103, 0xbfb8aa3b, v84
	v_exp_f32_e32 v105, v103
	s_nop 0
	v_pk_add_f32 v[104:105], v[104:105], 1.0 op_sel_hi:[1,0]
	s_nop 0
	v_rcp_f32_e32 v103, v105
	s_nop 0
	v_mul_f32_e32 v84, v84, v103
	v_rcp_f32_e32 v103, v104
	s_nop 0
	v_mul_f32_e32 v92, v92, v103
	v_exp_f32_e32 v104, v85
	v_and_b32_e32 v85, 0xffff0000, v96
	v_mul_f32_e32 v84, v92, v84
	v_mul_f32_e32 v92, 0xbfb8aa3b, v85
	v_exp_f32_e32 v105, v92
	s_nop 0
	v_pk_add_f32 v[104:105], v[104:105], 1.0 op_sel_hi:[1,0]
	s_nop 0
	v_rcp_f32_e32 v92, v105
	s_nop 0
	v_mul_f32_e32 v85, v85, v92
	v_rcp_f32_e32 v92, v104
	s_nop 0
	v_mul_f32_e32 v92, v93, v92
	v_mul_f32_e32 v85, v92, v85
	v_exp_f32_e32 v92, v86
	v_lshlrev_b32_e32 v86, 16, v97
	v_mul_f32_e32 v93, 0xbfb8aa3b, v86
	v_exp_f32_e32 v93, v93
	s_nop 0
	v_pk_add_f32 v[92:93], v[92:93], 1.0 op_sel_hi:[1,0]
	s_nop 0
	v_rcp_f32_e32 v96, v93
	s_nop 0
	v_mul_f32_e32 v86, v86, v96
	v_rcp_f32_e32 v92, v92
	s_nop 0
	v_mul_f32_e32 v92, v94, v92
	v_mul_f32_e32 v86, v92, v86
	v_exp_f32_e32 v92, v87
	v_and_b32_e32 v87, 0xffff0000, v97
	v_mul_f32_e32 v93, 0xbfb8aa3b, v87
	v_exp_f32_e32 v93, v93
	s_nop 0
	v_pk_add_f32 v[92:93], v[92:93], 1.0 op_sel_hi:[1,0]
	s_nop 0
	v_rcp_f32_e32 v94, v93
	s_nop 0
	v_mul_f32_e32 v87, v87, v94
	v_rcp_f32_e32 v92, v92
	s_nop 0
	v_mul_f32_e32 v92, v95, v92
	v_mul_f32_e32 v87, v92, v87
	v_exp_f32_e32 v92, v80
	v_lshlrev_b32_e32 v80, 16, v98
	v_mul_f32_e32 v93, 0xbfb8aa3b, v80
	v_exp_f32_e32 v93, v93
	s_nop 0
	v_pk_add_f32 v[92:93], v[92:93], 1.0 op_sel_hi:[1,0]
	s_nop 0
	v_rcp_f32_e32 v94, v93
	s_nop 0
	v_mul_f32_e32 v80, v80, v94
	v_rcp_f32_e32 v92, v92
	s_nop 0
	v_mul_f32_e32 v88, v88, v92
	v_and_b32_e32 v92, 0xffff0000, v98
	v_mul_f32_e32 v88, v88, v80
	v_mul_f32_e32 v80, 0xbfb8aa3b, v81
	v_mul_f32_e32 v81, 0xbfb8aa3b, v92
	v_exp_f32_e32 v80, v80
	v_exp_f32_e32 v81, v81
	s_nop 0
	v_pk_add_f32 v[80:81], v[80:81], 1.0 op_sel_hi:[1,0]
	s_nop 0
	v_rcp_f32_e32 v93, v81
; __device__ __forceinline__ unsigned cvt_pk_bf16(float lo, float hi) { unsigned r; asm volatile("v_cvt_pk_bf16_f32 %0, %1, %2" : "=v"(r) : "v"(lo), "v"(hi)); return r; }
; __device__ __forceinline__ float bflo(unsigned w) { return __uint_as_float(w << 16); }
; __device__ __forceinline__ float bfhi(unsigned w) { return __uint_as_float(w & 0xffff0000u); }
; __device__ __forceinline__ float silu_f(float z) { return z / (1.0f + __expf(-z)); }
; __device__ __forceinline__ float sigmoid_f(float z) { return 1.0f / (1.0f + __expf(-z)); }
;     __device__ __forceinline__ void operator()(const AccT& acc, const Unit& u, int wr, int wc, int fr, int fq) const {
;         bf16_t* OCAT = (bf16_t*)(ws + WS_H); const bf16_t* PROJ = (const bf16_t*)(ws + WS_PROJ);
;         const int lc = u.pn * 128 + wc * 32 + 8 * fq;
;         const f32x4 bl0 = *(const f32x4*)(bglu + lc), bl1 = *(const f32x4*)(bglu + lc + 4), bg0 = *(const f32x4*)(bglu + 1024 + lc), bg1 = *(const f32x4*)(bglu + 1024 + lc + 4);
; #pragma unroll
;         for (int ai = 0; ai < 2; ++ai)
; #pragma unroll
;             for (int m = 0; m < 4; ++m) {
;                 const int row = u.pm * 256 + ai * 128 + wr * 64 + m * 16 + fr;
;                 const u32x4 z = *(const u32x4*)(PROJ + (size_t)row * PP + C_ZS + lc);
;                 const f32x4 l0 = acc[ai][0][m][0] + bl0, l1 = acc[ai][0][m][1] + bl1, g0 = acc[ai][1][m][0] + bg0, g1 = acc[ai][1][m][1] + bg1;
;                 float o[8];
;                 o[0] = l0[0] * sigmoid_f(g0[0]) * silu_f(bflo(z.x)); o[1] = l0[1] * sigmoid_f(g0[1]) * silu_f(bfhi(z.x));
;                 o[2] = l0[2] * sigmoid_f(g0[2]) * silu_f(bflo(z.y)); o[3] = l0[3] * sigmoid_f(g0[3]) * silu_f(bfhi(z.y));
;                 o[4] = l1[0] * sigmoid_f(g1[0]) * silu_f(bflo(z.z)); o[5] = l1[1] * sigmoid_f(g1[1]) * silu_f(bfhi(z.z));
;                 o[6] = l1[2] * sigmoid_f(g1[2]) * silu_f(bflo(z.w)); o[7] = l1[3] * sigmoid_f(g1[3]) * silu_f(bfhi(z.w));
;                 u32x4 w; w.x = cvt_pk_bf16(o[0], o[1]); w.y = cvt_pk_bf16(o[2], o[3]); w.z = cvt_pk_bf16(o[4], o[5]); w.w = cvt_pk_bf16(o[6], o[7]);
;                 *(u32x4*)(OCAT + (size_t)row * 2048 + 1024 + lc) = w;
;                 if (m == 3) asm volatile("" ::: "memory");
;             }
;     }
	s_nop 0
	v_mul_f32_e32 v81, v92, v93
	v_rcp_f32_e32 v80, v80
	s_nop 0
	v_mul_f32_e32 v80, v89, v80
	v_mul_f32_e32 v89, v80, v81
	v_mul_f32_e32 v80, 0xbfb8aa3b, v82
	v_lshlrev_b32_e32 v82, 16, v99
	v_mul_f32_e32 v81, 0xbfb8aa3b, v82
	v_exp_f32_e32 v80, v80
	v_exp_f32_e32 v81, v81
	s_nop 0
	v_pk_add_f32 v[80:81], v[80:81], 1.0 op_sel_hi:[1,0]
	s_nop 0
	v_rcp_f32_e32 v92, v81
	s_nop 0
	v_mul_f32_e32 v81, v82, v92
	v_rcp_f32_e32 v80, v80
	s_nop 0
	v_mul_f32_e32 v80, v90, v80
	v_and_b32_e32 v82, 0xffff0000, v99
	v_mul_f32_e32 v90, v80, v81
	v_mul_f32_e32 v80, 0xbfb8aa3b, v83
	v_mul_f32_e32 v81, 0xbfb8aa3b, v82
	v_exp_f32_e32 v80, v80
	v_exp_f32_e32 v81, v81
	s_nop 0
	v_pk_add_f32 v[80:81], v[80:81], 1.0 op_sel_hi:[1,0]
	s_nop 0
	v_rcp_f32_e32 v83, v81
	s_nop 0
	v_mul_f32_e32 v81, v82, v83
	v_rcp_f32_e32 v80, v80
	s_nop 0
	v_mul_f32_e32 v80, v91, v80
	v_mul_f32_e32 v83, v80, v81
	v_cvt_pk_bf16_f32 v80, v84, v85
	v_mad_i64_i32 v[84:85], s[30:31], v102, s66, v[100:101]
	v_lshl_add_u64 v[84:85], v[84:85], 0, v[158:159]
	v_add_co_u32_e32 v84, vcc, s67, v84
	v_cvt_pk_bf16_f32 v81, v86, v87
	v_add_u32_e32 v86, 0x80, v168
	s_nop 0
	v_addc_co_u32_e32 v85, vcc, 0, v85, vcc
	v_cvt_pk_bf16_f32 v82, v88, v89
	v_cvt_pk_bf16_f32 v83, v90, v83
	global_store_dwordx4 v[84:85], v[80:83], off offset:2048
	v_mad_i64_i32 v[84:85], s[30:31], v86, s52, v[160:161]
	s_nop 0
	v_lshl_add_u64 v[80:81], v[84:85], 0, v[158:159]
	v_add_co_u32_e32 v80, vcc, s63, v80
	v_exp_f32_e32 v88, v68
	s_nop 0
	v_addc_co_u32_e32 v81, vcc, 0, v81, vcc
	global_load_dwordx4 v[80:83], v[80:81], off
	s_waitcnt vmcnt(0)
	v_lshlrev_b32_e32 v68, 16, v80
	v_mul_f32_e32 v87, 0xbfb8aa3b, v68
	v_exp_f32_e32 v89, v87
	s_nop 0
	v_pk_add_f32 v[88:89], v[88:89], 1.0 op_sel_hi:[1,0]
	s_nop 0
	v_rcp_f32_e32 v87, v89
	s_nop 0
	v_mul_f32_e32 v68, v68, v87
	v_rcp_f32_e32 v87, v88
	s_nop 0
	v_mul_f32_e32 v76, v76, v87
	v_exp_f32_e32 v88, v69
	v_and_b32_e32 v69, 0xffff0000, v80
	v_mul_f32_e32 v68, v76, v68
	v_mul_f32_e32 v76, 0xbfb8aa3b, v69
	v_exp_f32_e32 v89, v76
	s_nop 0
	v_pk_add_f32 v[88:89], v[88:89], 1.0 op_sel_hi:[1,0]
	s_nop 0
	v_rcp_f32_e32 v76, v89
	s_nop 0
	v_mul_f32_e32 v69, v69, v76
	v_rcp_f32_e32 v76, v88
	s_nop 0
	v_mul_f32_e32 v76, v77, v76
	v_mul_f32_e32 v69, v76, v69
	v_exp_f32_e32 v76, v70
	v_lshlrev_b32_e32 v70, 16, v81
	v_mul_f32_e32 v77, 0xbfb8aa3b, v70
	v_exp_f32_e32 v77, v77
	s_nop 0
	v_pk_add_f32 v[76:77], v[76:77], 1.0 op_sel_hi:[1,0]
	s_nop 0
	v_rcp_f32_e32 v80, v77
	s_nop 0
	v_mul_f32_e32 v70, v70, v80
	v_rcp_f32_e32 v76, v76
	s_nop 0
	v_mul_f32_e32 v76, v78, v76
	v_mul_f32_e32 v70, v76, v70
	v_exp_f32_e32 v76, v71
	v_and_b32_e32 v71, 0xffff0000, v81
	v_mul_f32_e32 v77, 0xbfb8aa3b, v71
	v_exp_f32_e32 v77, v77
	s_nop 0
	v_pk_add_f32 v[76:77], v[76:77], 1.0 op_sel_hi:[1,0]
	s_nop 0
	v_rcp_f32_e32 v78, v77
	s_nop 0
	v_mul_f32_e32 v71, v71, v78
	v_rcp_f32_e32 v76, v76
	s_nop 0
	v_mul_f32_e32 v76, v79, v76
	v_mul_f32_e32 v71, v76, v71
	v_exp_f32_e32 v76, v64
	v_lshlrev_b32_e32 v64, 16, v82
	v_mul_f32_e32 v77, 0xbfb8aa3b, v64
	v_exp_f32_e32 v77, v77
	s_nop 0
	v_pk_add_f32 v[76:77], v[76:77], 1.0 op_sel_hi:[1,0]
	s_nop 0
	v_rcp_f32_e32 v78, v77
	s_nop 0
	v_mul_f32_e32 v64, v64, v78
	v_rcp_f32_e32 v76, v76
	s_nop 0
	v_mul_f32_e32 v72, v72, v76
	v_and_b32_e32 v76, 0xffff0000, v82
	v_mul_f32_e32 v72, v72, v64
	v_mul_f32_e32 v64, 0xbfb8aa3b, v65
	v_mul_f32_e32 v65, 0xbfb8aa3b, v76
	v_exp_f32_e32 v64, v64
	v_exp_f32_e32 v65, v65
	s_nop 0
	v_pk_add_f32 v[64:65], v[64:65], 1.0 op_sel_hi:[1,0]
	s_nop 0
	v_rcp_f32_e32 v77, v65
	s_nop 0
	v_mul_f32_e32 v65, v76, v77
	v_rcp_f32_e32 v64, v64
	s_nop 0
	v_mul_f32_e32 v64, v73, v64
	v_mul_f32_e32 v73, v64, v65
	v_mul_f32_e32 v64, 0xbfb8aa3b, v66
	v_lshlrev_b32_e32 v66, 16, v83
	v_mul_f32_e32 v65, 0xbfb8aa3b, v66
	v_exp_f32_e32 v64, v64
	v_exp_f32_e32 v65, v65
	s_nop 0
	v_pk_add_f32 v[64:65], v[64:65], 1.0 op_sel_hi:[1,0]
	s_nop 0
	v_rcp_f32_e32 v76, v65
	s_nop 0
	v_mul_f32_e32 v65, v66, v76
	v_rcp_f32_e32 v64, v64
	s_nop 0
	v_mul_f32_e32 v64, v74, v64
	v_and_b32_e32 v66, 0xffff0000, v83
	v_mul_f32_e32 v74, v64, v65
	v_mul_f32_e32 v64, 0xbfb8aa3b, v67
	v_mul_f32_e32 v65, 0xbfb8aa3b, v66
	v_exp_f32_e32 v64, v64
	v_exp_f32_e32 v65, v65
	s_nop 0
	v_pk_add_f32 v[64:65], v[64:65], 1.0 op_sel_hi:[1,0]
	s_nop 0
	v_rcp_f32_e32 v67, v65
	s_nop 0
	v_mul_f32_e32 v65, v66, v67
	v_rcp_f32_e32 v64, v64
	s_nop 0
	v_mul_f32_e32 v64, v75, v64
	v_mul_f32_e32 v67, v64, v65
	v_cvt_pk_bf16_f32 v64, v68, v69
	v_mad_i64_i32 v[68:69], s[30:31], v86, s66, v[84:85]
	v_lshl_add_u64 v[68:69], v[68:69], 0, v[158:159]
	v_add_co_u32_e32 v68, vcc, s67, v68
	v_cvt_pk_bf16_f32 v65, v70, v71
	v_add_u32_e32 v70, 0x90, v168
	s_nop 0
	v_addc_co_u32_e32 v69, vcc, 0, v69, vcc
	v_cvt_pk_bf16_f32 v66, v72, v73
	v_cvt_pk_bf16_f32 v67, v74, v67
	global_store_dwordx4 v[68:69], v[64:67], off offset:2048
	v_mad_i64_i32 v[68:69], s[30:31], v70, s52, v[160:161]
	s_nop 0
	v_lshl_add_u64 v[64:65], v[68:69], 0, v[158:159]
	v_add_co_u32_e32 v64, vcc, s63, v64
	v_exp_f32_e32 v72, v52
	s_nop 0
	v_addc_co_u32_e32 v65, vcc, 0, v65, vcc
	global_load_dwordx4 v[64:67], v[64:65], off
	s_waitcnt vmcnt(0)
; __device__ __forceinline__ unsigned cvt_pk_bf16(float lo, float hi) { unsigned r; asm volatile("v_cvt_pk_bf16_f32 %0, %1, %2" : "=v"(r) : "v"(lo), "v"(hi)); return r; }
; __device__ __forceinline__ float bflo(unsigned w) { return __uint_as_float(w << 16); }
; __device__ __forceinline__ float bfhi(unsigned w) { return __uint_as_float(w & 0xffff0000u); }
; __device__ __forceinline__ float silu_f(float z) { return z / (1.0f + __expf(-z)); }
; __device__ __forceinline__ float sigmoid_f(float z) { return 1.0f / (1.0f + __expf(-z)); }
;     __device__ __forceinline__ void operator()(const AccT& acc, const Unit& u, int wr, int wc, int fr, int fq) const {
;         bf16_t* OCAT = (bf16_t*)(ws + WS_H); const bf16_t* PROJ = (const bf16_t*)(ws + WS_PROJ);
;         const int lc = u.pn * 128 + wc * 32 + 8 * fq;
;         const f32x4 bl0 = *(const f32x4*)(bglu + lc), bl1 = *(const f32x4*)(bglu + lc + 4), bg0 = *(const f32x4*)(bglu + 1024 + lc), bg1 = *(const f32x4*)(bglu + 1024 + lc + 4);
; #pragma unroll
;         for (int ai = 0; ai < 2; ++ai)
; #pragma unroll
;             for (int m = 0; m < 4; ++m) {
;                 const int row = u.pm * 256 + ai * 128 + wr * 64 + m * 16 + fr;
;                 const u32x4 z = *(const u32x4*)(PROJ + (size_t)row * PP + C_ZS + lc);
;                 const f32x4 l0 = acc[ai][0][m][0] + bl0, l1 = acc[ai][0][m][1] + bl1, g0 = acc[ai][1][m][0] + bg0, g1 = acc[ai][1][m][1] + bg1;
;                 float o[8];
;                 o[0] = l0[0] * sigmoid_f(g0[0]) * silu_f(bflo(z.x)); o[1] = l0[1] * sigmoid_f(g0[1]) * silu_f(bfhi(z.x));
;                 o[2] = l0[2] * sigmoid_f(g0[2]) * silu_f(bflo(z.y)); o[3] = l0[3] * sigmoid_f(g0[3]) * silu_f(bfhi(z.y));
;                 o[4] = l1[0] * sigmoid_f(g1[0]) * silu_f(bflo(z.z)); o[5] = l1[1] * sigmoid_f(g1[1]) * silu_f(bfhi(z.z));
;                 o[6] = l1[2] * sigmoid_f(g1[2]) * silu_f(bflo(z.w)); o[7] = l1[3] * sigmoid_f(g1[3]) * silu_f(bfhi(z.w));
;                 u32x4 w; w.x = cvt_pk_bf16(o[0], o[1]); w.y = cvt_pk_bf16(o[2], o[3]); w.z = cvt_pk_bf16(o[4], o[5]); w.w = cvt_pk_bf16(o[6], o[7]);
;                 *(u32x4*)(OCAT + (size_t)row * 2048 + 1024 + lc) = w;
;                 if (m == 3) asm volatile("" ::: "memory");
;             }
;     }
	v_lshlrev_b32_e32 v52, 16, v64
	v_mul_f32_e32 v71, 0xbfb8aa3b, v52
	v_exp_f32_e32 v73, v71
	s_nop 0
	v_pk_add_f32 v[72:73], v[72:73], 1.0 op_sel_hi:[1,0]
	s_nop 0
	v_rcp_f32_e32 v71, v73
	s_nop 0
	v_mul_f32_e32 v52, v52, v71
	v_rcp_f32_e32 v71, v72
	s_nop 0
	v_mul_f32_e32 v60, v60, v71
	v_exp_f32_e32 v72, v53
	v_and_b32_e32 v53, 0xffff0000, v64
	v_mul_f32_e32 v52, v60, v52
	v_mul_f32_e32 v60, 0xbfb8aa3b, v53
	v_exp_f32_e32 v73, v60
	s_nop 0
	v_pk_add_f32 v[72:73], v[72:73], 1.0 op_sel_hi:[1,0]
	s_nop 0
	v_rcp_f32_e32 v60, v73
	s_nop 0
	v_mul_f32_e32 v53, v53, v60
	v_rcp_f32_e32 v60, v72
	s_nop 0
	v_mul_f32_e32 v60, v61, v60
	v_mul_f32_e32 v53, v60, v53
	v_exp_f32_e32 v60, v54
	v_lshlrev_b32_e32 v54, 16, v65
	v_mul_f32_e32 v61, 0xbfb8aa3b, v54
	v_exp_f32_e32 v61, v61
	s_nop 0
	v_pk_add_f32 v[60:61], v[60:61], 1.0 op_sel_hi:[1,0]
	s_nop 0
	v_rcp_f32_e32 v64, v61
	s_nop 0
	v_mul_f32_e32 v54, v54, v64
	v_rcp_f32_e32 v60, v60
	s_nop 0
	v_mul_f32_e32 v60, v62, v60
	v_mul_f32_e32 v54, v60, v54
	v_exp_f32_e32 v60, v55
	v_and_b32_e32 v55, 0xffff0000, v65
	v_mul_f32_e32 v61, 0xbfb8aa3b, v55
	v_exp_f32_e32 v61, v61
	s_nop 0
	v_pk_add_f32 v[60:61], v[60:61], 1.0 op_sel_hi:[1,0]
	s_nop 0
	v_rcp_f32_e32 v62, v61
	s_nop 0
	v_mul_f32_e32 v55, v55, v62
	v_rcp_f32_e32 v60, v60
	s_nop 0
	v_mul_f32_e32 v60, v63, v60
	v_mul_f32_e32 v55, v60, v55
	v_exp_f32_e32 v60, v48
	v_lshlrev_b32_e32 v48, 16, v66
	v_mul_f32_e32 v61, 0xbfb8aa3b, v48
	v_exp_f32_e32 v61, v61
	s_nop 0
	v_pk_add_f32 v[60:61], v[60:61], 1.0 op_sel_hi:[1,0]
	s_nop 0
	v_rcp_f32_e32 v62, v61
	s_nop 0
	v_mul_f32_e32 v48, v48, v62
	v_rcp_f32_e32 v60, v60
	s_nop 0
	v_mul_f32_e32 v56, v56, v60
	v_and_b32_e32 v60, 0xffff0000, v66
	v_mul_f32_e32 v56, v56, v48
	v_mul_f32_e32 v48, 0xbfb8aa3b, v49
	v_mul_f32_e32 v49, 0xbfb8aa3b, v60
	v_exp_f32_e32 v48, v48
	v_exp_f32_e32 v49, v49
	s_nop 0
	v_pk_add_f32 v[48:49], v[48:49], 1.0 op_sel_hi:[1,0]
	s_nop 0
	v_rcp_f32_e32 v61, v49
	s_nop 0
	v_mul_f32_e32 v49, v60, v61
	v_rcp_f32_e32 v48, v48
	s_nop 0
	v_mul_f32_e32 v48, v57, v48
	v_mul_f32_e32 v57, v48, v49
	v_mul_f32_e32 v48, 0xbfb8aa3b, v50
	v_lshlrev_b32_e32 v50, 16, v67
	v_mul_f32_e32 v49, 0xbfb8aa3b, v50
	v_exp_f32_e32 v48, v48
	v_exp_f32_e32 v49, v49
	s_nop 0
	v_pk_add_f32 v[48:49], v[48:49], 1.0 op_sel_hi:[1,0]
	s_nop 0
	v_rcp_f32_e32 v60, v49
	s_nop 0
	v_mul_f32_e32 v49, v50, v60
	v_rcp_f32_e32 v48, v48
	s_nop 0
	v_mul_f32_e32 v48, v58, v48
	v_and_b32_e32 v50, 0xffff0000, v67
	v_mul_f32_e32 v58, v48, v49
	v_mul_f32_e32 v48, 0xbfb8aa3b, v51
	v_mul_f32_e32 v49, 0xbfb8aa3b, v50
	v_exp_f32_e32 v48, v48
	v_exp_f32_e32 v49, v49
	s_nop 0
	v_pk_add_f32 v[48:49], v[48:49], 1.0 op_sel_hi:[1,0]
	s_nop 0
	v_rcp_f32_e32 v51, v49
	s_nop 0
	v_mul_f32_e32 v49, v50, v51
	v_rcp_f32_e32 v48, v48
	s_nop 0
	v_mul_f32_e32 v48, v59, v48
	v_mul_f32_e32 v51, v48, v49
	v_cvt_pk_bf16_f32 v48, v52, v53
	v_mad_i64_i32 v[52:53], s[30:31], v70, s66, v[68:69]
	v_lshl_add_u64 v[52:53], v[52:53], 0, v[158:159]
	v_add_co_u32_e32 v52, vcc, s67, v52
	v_cvt_pk_bf16_f32 v49, v54, v55
	v_add_u32_e32 v54, 0xa0, v168
	s_nop 0
	v_addc_co_u32_e32 v53, vcc, 0, v53, vcc
	v_cvt_pk_bf16_f32 v50, v56, v57
	v_cvt_pk_bf16_f32 v51, v58, v51
	global_store_dwordx4 v[52:53], v[48:51], off offset:2048
	v_mad_i64_i32 v[52:53], s[30:31], v54, s52, v[160:161]
	s_nop 0
	v_lshl_add_u64 v[48:49], v[52:53], 0, v[158:159]
	v_add_co_u32_e32 v48, vcc, s63, v48
	v_exp_f32_e32 v56, v36
	s_nop 0
	v_addc_co_u32_e32 v49, vcc, 0, v49, vcc
	global_load_dwordx4 v[48:51], v[48:49], off
	s_waitcnt vmcnt(0)
; template <bool SP2 = true, class Epi, class Sched>
; __device__ __forceinline__ void gemm_phase(LAS unsigned char* lds, const int K, const int lda, const int ldb, const Sched& S, const Epi& E) {
;     ...
;         if constexpr (Epi::FUSED) E.fused(acc, cur, wr, wc, fr, fq, lds, tid); else E(acc, cur, wr, wc, fr, fq);
;         if (!has_next) break;
; #pragma unroll
;         for (int a = 0; a < 2; ++a)
; #pragma unroll
;             for (int b = 0; b < 2; ++b)
; #pragma unroll
;                 for (int m = 0; m < 4; ++m)
; #pragma unroll
;                     for (int n = 0; n < 2; ++n) acc[a][b][m][n] = (f32x4){0.f, 0.f, 0.f, 0.f};
;     __device__ __forceinline__ void operator()(const AccT& acc, const Unit& u, int wr, int wc, int fr, int fq) const {
;         bf16_t* OCAT = (bf16_t*)(ws + WS_H); const bf16_t* PROJ = (const bf16_t*)(ws + WS_PROJ);
;         const int lc = u.pn * 128 + wc * 32 + 8 * fq;
;         const f32x4 bl0 = *(const f32x4*)(bglu + lc), bl1 = *(const f32x4*)(bglu + lc + 4), bg0 = *(const f32x4*)(bglu + 1024 + lc), bg1 = *(const f32x4*)(bglu + 1024 + lc + 4);
; #pragma unroll
;         for (int ai = 0; ai < 2; ++ai)
; #pragma unroll
;             for (int m = 0; m < 4; ++m) {
;                 const int row = u.pm * 256 + ai * 128 + wr * 64 + m * 16 + fr;
;                 const u32x4 z = *(const u32x4*)(PROJ + (size_t)row * PP + C_ZS + lc);
;                 const f32x4 l0 = acc[ai][0][m][0] + bl0, l1 = acc[ai][0][m][1] + bl1, g0 = acc[ai][1][m][0] + bg0, g1 = acc[ai][1][m][1] + bg1;
;                 float o[8];
;                 o[0] = l0[0] * sigmoid_f(g0[0]) * silu_f(bflo(z.x)); o[1] = l0[1] * sigmoid_f(g0[1]) * silu_f(bfhi(z.x));
;                 o[2] = l0[2] * sigmoid_f(g0[2]) * silu_f(bflo(z.y)); o[3] = l0[3] * sigmoid_f(g0[3]) * silu_f(bfhi(z.y));
;                 o[4] = l1[0] * sigmoid_f(g1[0]) * silu_f(bflo(z.z)); o[5] = l1[1] * sigmoid_f(g1[1]) * silu_f(bfhi(z.z));
;                 o[6] = l1[2] * sigmoid_f(g1[2]) * silu_f(bflo(z.w)); o[7] = l1[3] * sigmoid_f(g1[3]) * silu_f(bfhi(z.w));
;                 u32x4 w; w.x = cvt_pk_bf16(o[0], o[1]); w.y = cvt_pk_bf16(o[2], o[3]); w.z = cvt_pk_bf16(o[4], o[5]); w.w = cvt_pk_bf16(o[6], o[7]);
;                 *(u32x4*)(OCAT + (size_t)row * 2048 + 1024 + lc) = w;
;                 if (m == 3) asm volatile("" ::: "memory");
;             }
;     }
	v_lshlrev_b32_e32 v36, 16, v48
	v_mul_f32_e32 v55, 0xbfb8aa3b, v36
	v_exp_f32_e32 v57, v55
	s_nop 0
	v_pk_add_f32 v[56:57], v[56:57], 1.0 op_sel_hi:[1,0]
	s_nop 0
	v_rcp_f32_e32 v55, v57
	s_nop 0
	v_mul_f32_e32 v36, v36, v55
	v_rcp_f32_e32 v55, v56
	s_nop 0
	v_mul_f32_e32 v44, v44, v55
	v_exp_f32_e32 v56, v37
	v_and_b32_e32 v37, 0xffff0000, v48
	v_mul_f32_e32 v36, v44, v36
	v_mul_f32_e32 v44, 0xbfb8aa3b, v37
	v_exp_f32_e32 v57, v44
	s_nop 0
	v_pk_add_f32 v[56:57], v[56:57], 1.0 op_sel_hi:[1,0]
	s_nop 0
	v_rcp_f32_e32 v44, v57
	s_nop 0
	v_mul_f32_e32 v37, v37, v44
	v_rcp_f32_e32 v44, v56
	s_nop 0
	v_mul_f32_e32 v44, v45, v44
	v_mul_f32_e32 v37, v44, v37
	v_exp_f32_e32 v44, v38
	v_lshlrev_b32_e32 v38, 16, v49
	v_mul_f32_e32 v45, 0xbfb8aa3b, v38
	v_exp_f32_e32 v45, v45
	s_nop 0
	v_pk_add_f32 v[44:45], v[44:45], 1.0 op_sel_hi:[1,0]
	s_nop 0
	v_rcp_f32_e32 v48, v45
	s_nop 0
	v_mul_f32_e32 v38, v38, v48
	v_rcp_f32_e32 v44, v44
	s_nop 0
	v_mul_f32_e32 v44, v46, v44
	v_mul_f32_e32 v38, v44, v38
	v_exp_f32_e32 v44, v39
	v_and_b32_e32 v39, 0xffff0000, v49
	v_mul_f32_e32 v45, 0xbfb8aa3b, v39
	v_exp_f32_e32 v45, v45
	s_nop 0
	v_pk_add_f32 v[44:45], v[44:45], 1.0 op_sel_hi:[1,0]
	s_nop 0
	v_rcp_f32_e32 v46, v45
	s_nop 0
	v_mul_f32_e32 v39, v39, v46
	v_rcp_f32_e32 v44, v44
	s_nop 0
	v_mul_f32_e32 v44, v47, v44
	v_mul_f32_e32 v39, v44, v39
	v_exp_f32_e32 v44, v32
	v_lshlrev_b32_e32 v32, 16, v50
	v_mul_f32_e32 v45, 0xbfb8aa3b, v32
	v_exp_f32_e32 v45, v45
	s_nop 0
	v_pk_add_f32 v[44:45], v[44:45], 1.0 op_sel_hi:[1,0]
	s_nop 0
	v_rcp_f32_e32 v46, v45
	s_nop 0
	v_mul_f32_e32 v32, v32, v46
	v_rcp_f32_e32 v44, v44
	s_nop 0
	v_mul_f32_e32 v40, v40, v44
	v_and_b32_e32 v44, 0xffff0000, v50
	v_mul_f32_e32 v40, v40, v32
	v_mul_f32_e32 v32, 0xbfb8aa3b, v33
	v_mul_f32_e32 v33, 0xbfb8aa3b, v44
	v_exp_f32_e32 v32, v32
	v_exp_f32_e32 v33, v33
	s_nop 0
	v_pk_add_f32 v[32:33], v[32:33], 1.0 op_sel_hi:[1,0]
	s_nop 0
	v_rcp_f32_e32 v45, v33
	s_nop 0
	v_mul_f32_e32 v33, v44, v45
	v_rcp_f32_e32 v32, v32
	s_nop 0
	v_mul_f32_e32 v32, v41, v32
	v_mul_f32_e32 v41, v32, v33
	v_mul_f32_e32 v32, 0xbfb8aa3b, v34
	v_lshlrev_b32_e32 v34, 16, v51
	v_mul_f32_e32 v33, 0xbfb8aa3b, v34
	v_exp_f32_e32 v32, v32
	v_exp_f32_e32 v33, v33
	s_nop 0
	v_pk_add_f32 v[32:33], v[32:33], 1.0 op_sel_hi:[1,0]
	s_nop 0
	v_rcp_f32_e32 v44, v33
	s_nop 0
	v_mul_f32_e32 v33, v34, v44
	v_rcp_f32_e32 v32, v32
	s_nop 0
	v_mul_f32_e32 v32, v42, v32
	v_and_b32_e32 v34, 0xffff0000, v51
	v_mul_f32_e32 v42, v32, v33
	v_mul_f32_e32 v32, 0xbfb8aa3b, v35
	v_mul_f32_e32 v33, 0xbfb8aa3b, v34
	v_exp_f32_e32 v32, v32
	v_exp_f32_e32 v33, v33
	s_nop 0
	v_pk_add_f32 v[32:33], v[32:33], 1.0 op_sel_hi:[1,0]
	s_nop 0
	v_rcp_f32_e32 v35, v33
	s_nop 0
	v_mul_f32_e32 v33, v34, v35
	v_rcp_f32_e32 v32, v32
	s_nop 0
	v_mul_f32_e32 v32, v43, v32
	v_mul_f32_e32 v35, v32, v33
	v_cvt_pk_bf16_f32 v32, v36, v37
	v_mad_i64_i32 v[36:37], s[30:31], v54, s66, v[52:53]
	v_lshl_add_u64 v[36:37], v[36:37], 0, v[158:159]
	v_add_co_u32_e32 v36, vcc, s67, v36
	v_cvt_pk_bf16_f32 v33, v38, v39
	v_add_u32_e32 v38, 0xb0, v168
	s_nop 0
	v_addc_co_u32_e32 v37, vcc, 0, v37, vcc
	v_cvt_pk_bf16_f32 v34, v40, v41
	v_cvt_pk_bf16_f32 v35, v42, v35
	global_store_dwordx4 v[36:37], v[32:35], off offset:2048
	v_mad_i64_i32 v[36:37], s[30:31], v38, s52, v[160:161]
	s_nop 0
	v_lshl_add_u64 v[32:33], v[36:37], 0, v[158:159]
	v_add_co_u32_e32 v32, vcc, s63, v32
	s_nop 1
	v_addc_co_u32_e32 v33, vcc, 0, v33, vcc
	global_load_dwordx4 v[32:35], v[32:33], off
	s_waitcnt vmcnt(0)
	v_lshlrev_b32_e32 v4, 16, v32
	v_mul_f32_e32 v17, 0xbfb8aa3b, v4
	v_exp_f32_e32 v17, v17
	s_nop 0
	v_pk_add_f32 v[16:17], v[16:17], 1.0 op_sel_hi:[1,0]
	s_nop 0
	v_rcp_f32_e32 v18, v17
	s_nop 0
	v_mul_f32_e32 v4, v4, v18
	v_rcp_f32_e32 v16, v16
	s_nop 0
	v_mul_f32_e32 v12, v12, v16
	v_exp_f32_e32 v16, v5
	v_and_b32_e32 v5, 0xffff0000, v32
	v_mul_f32_e32 v4, v12, v4
	v_mul_f32_e32 v12, 0xbfb8aa3b, v5
	v_exp_f32_e32 v17, v12
	s_nop 0
	v_pk_add_f32 v[16:17], v[16:17], 1.0 op_sel_hi:[1,0]
	s_nop 0
	v_rcp_f32_e32 v12, v17
	s_nop 0
	v_mul_f32_e32 v5, v5, v12
	v_rcp_f32_e32 v12, v16
	s_nop 0
	v_mul_f32_e32 v12, v13, v12
	v_mul_f32_e32 v5, v12, v5
	v_exp_f32_e32 v12, v6
	v_lshlrev_b32_e32 v6, 16, v33
	v_mul_f32_e32 v13, 0xbfb8aa3b, v6
	v_exp_f32_e32 v13, v13
	s_nop 0
	v_pk_add_f32 v[12:13], v[12:13], 1.0 op_sel_hi:[1,0]
	s_nop 0
	v_rcp_f32_e32 v16, v13
	s_nop 0
	v_mul_f32_e32 v6, v6, v16
	v_rcp_f32_e32 v12, v12
	s_nop 0
	v_mul_f32_e32 v12, v14, v12
	v_mul_f32_e32 v6, v12, v6
	v_exp_f32_e32 v12, v7
	v_and_b32_e32 v7, 0xffff0000, v33
	v_mul_f32_e32 v13, 0xbfb8aa3b, v7
	v_exp_f32_e32 v13, v13
	s_nop 0
	v_pk_add_f32 v[12:13], v[12:13], 1.0 op_sel_hi:[1,0]
	s_nop 0
	v_rcp_f32_e32 v14, v13
	s_nop 0
	v_mul_f32_e32 v7, v7, v14
	v_rcp_f32_e32 v12, v12
	s_nop 0
	v_mul_f32_e32 v12, v15, v12
	v_mul_f32_e32 v7, v12, v7
	v_exp_f32_e32 v12, v0
	v_lshlrev_b32_e32 v0, 16, v34
	v_mul_f32_e32 v13, 0xbfb8aa3b, v0
	v_exp_f32_e32 v13, v13
	s_nop 0
	v_pk_add_f32 v[12:13], v[12:13], 1.0 op_sel_hi:[1,0]
	s_nop 0
	v_rcp_f32_e32 v14, v13
	s_nop 0
	v_mul_f32_e32 v0, v0, v14
	v_rcp_f32_e32 v12, v12
	s_nop 0
	v_mul_f32_e32 v8, v8, v12
	v_and_b32_e32 v12, 0xffff0000, v34
	v_mul_f32_e32 v8, v8, v0
	v_mul_f32_e32 v0, 0xbfb8aa3b, v1
	v_mul_f32_e32 v1, 0xbfb8aa3b, v12
	v_exp_f32_e32 v0, v0
	v_exp_f32_e32 v1, v1
	s_nop 0
	v_pk_add_f32 v[0:1], v[0:1], 1.0 op_sel_hi:[1,0]
	s_nop 0
	v_rcp_f32_e32 v13, v1
	s_nop 0
	v_mul_f32_e32 v1, v12, v13
	v_rcp_f32_e32 v0, v0
	s_nop 0
	v_mul_f32_e32 v0, v9, v0
	v_mul_f32_e32 v9, v0, v1
	v_mul_f32_e32 v0, 0xbfb8aa3b, v2
	v_lshlrev_b32_e32 v2, 16, v35
	v_mul_f32_e32 v1, 0xbfb8aa3b, v2
	v_exp_f32_e32 v0, v0
	v_exp_f32_e32 v1, v1
	s_nop 0
	v_pk_add_f32 v[0:1], v[0:1], 1.0 op_sel_hi:[1,0]
	s_nop 0
	v_rcp_f32_e32 v12, v1
	s_nop 0
	v_mul_f32_e32 v1, v2, v12
	v_rcp_f32_e32 v0, v0
	s_nop 0
	v_mul_f32_e32 v0, v10, v0
	v_and_b32_e32 v2, 0xffff0000, v35
	v_mul_f32_e32 v10, v0, v1
	v_mul_f32_e32 v0, 0xbfb8aa3b, v3
	v_mul_f32_e32 v1, 0xbfb8aa3b, v2
	v_exp_f32_e32 v0, v0
	v_exp_f32_e32 v1, v1
	s_nop 0
	v_pk_add_f32 v[0:1], v[0:1], 1.0 op_sel_hi:[1,0]
	s_nop 0
	v_rcp_f32_e32 v3, v1
	s_nop 0
	v_mul_f32_e32 v1, v2, v3
	v_rcp_f32_e32 v0, v0
	s_nop 0
	v_mul_f32_e32 v0, v11, v0
	v_mul_f32_e32 v3, v0, v1
	v_cvt_pk_bf16_f32 v0, v4, v5
	v_mad_i64_i32 v[4:5], s[30:31], v38, s66, v[36:37]
	v_lshl_add_u64 v[4:5], v[4:5], 0, v[158:159]
	v_add_co_u32_e32 v4, vcc, 0xca00000, v4
	v_cvt_pk_bf16_f32 v1, v6, v7
	v_cvt_pk_bf16_f32 v2, v8, v9
	v_cvt_pk_bf16_f32 v3, v10, v3
	s_mov_b64 s[30:31], -1
	s_nop 0
	v_addc_co_u32_e32 v5, vcc, 0, v5, vcc
	global_store_dwordx4 v[4:5], v[0:3], off offset:2048
	s_andn2_b64 vcc, exec, s[4:5]
	s_cbranch_vccnz .LBB0_598
	s_andn2_b64 vcc, exec, s[8:9]
	s_cbranch_vccnz .LBB0_597
	s_barrier
	s_branch .LBB0_597
